# v014 + GEMM K-loops: skip the first two vmcnt waits of a unit that follows an epilogue (flag in a free SGPR)
# baseline (speedup 1.0000x reference)
.LBB0_99:
	s_load_dwordx2 s[2:3], s[0:1], 0x108
	s_waitcnt lgkmcnt(0)
	s_cmp_lt_i32 s2, 2
	s_cselect_b64 s[2:3], -1, 0
	s_add_u32 s6, s92, 0x14600000
	s_addc_u32 s7, s93, 0
	v_writelane_b32 v254, s6, 30
	s_and_b64 s[2:3], s[2:3], s[4:5]
	s_andn2_b64 vcc, exec, s[2:3]
	v_writelane_b32 v254, s7, 31
	s_cbranch_vccnz .LBB0_130
	s_mov_b32 s32, 0
	s_waitcnt vmcnt(10)
	v_mov_b32_e32 v10, v0
	s_cmpk_gt_i32 s86, 0xc70
	v_readfirstlane_b32 s7, v10
	s_cbranch_scc1 .LBB0_130
	s_ashr_i32 s33, s86, 31
	s_lshr_b32 s4, s33, 29
	s_add_i32 s8, s86, s4
	s_and_b32 s4, s8, -8
	s_sub_i32 s9, s86, s4
	s_cmp_gt_i32 s9, 0
	s_cbranch_scc0 .LBB0_103
	s_mul_i32 s4, s9, 0x18e
	s_or_b32 s6, s4, 1
	s_cbranch_execz .LBB0_104
	s_branch .LBB0_105

.LBB0_117:
	ds_read_b128 v[130:133], v161
	ds_read_b128 v[134:137], v161 offset:1024
	ds_read_b128 v[170:173], v161 offset:2048
	ds_read_b128 v[174:177], v161 offset:3072
	ds_read_b128 v[178:181], v163
	ds_read_b128 v[182:185], v163 offset:1024
	ds_read_b128 v[186:189], v163 offset:2048
	ds_read_b128 v[190:193], v163 offset:3072
	s_add_u32 s50, s48, 0xfff80080
	s_addc_u32 s51, s49, -1
	s_cmp_eq_u32 s74, 28
	s_cselect_b32 s53, s9, s51
	s_cselect_b32 s52, s43, s50
	s_cselect_b32 s51, s41, s73
	s_cselect_b32 s50, s71, s72
	v_lshl_add_u64 v[154:155], s[48:49], 0, v[146:147]
	s_add_i32 m0, s56, 0xc000
	ds_read_b128 v[194:197], v165
	ds_read_b128 v[198:201], v165 offset:1024
	ds_read_b128 v[202:205], v165 offset:2048
	ds_read_b128 v[206:209], v165 offset:3072
	ds_read_b128 v[210:213], v165 offset:4096
	ds_read_b128 v[214:217], v165 offset:5120
	ds_read_b128 v[218:221], v165 offset:6144
	ds_read_b128 v[222:225], v165 offset:7168
	global_load_lds_dwordx4 v[154:155], off
	v_lshl_add_u64 v[154:155], s[48:49], 0, v[148:149]
	s_add_i32 m0, s56, 0xe000
	s_nop 0
	global_load_lds_dwordx4 v[154:155], off
	s_cmp_lg_u32 s32, 0
	s_cbranch_scc1 .Lkw_P1_1
	s_waitcnt vmcnt(8)
.Lkw_P1_1:
	s_waitcnt lgkmcnt(0)
	s_barrier
	s_setprio 1
	s_waitcnt lgkmcnt(0)
	v_mfma_f32_16x16x32_bf16 v[126:129], v[130:133], v[194:197], v[126:129]
	v_mfma_f32_16x16x32_bf16 v[122:125], v[170:173], v[194:197], v[122:125]
	v_mfma_f32_16x16x32_bf16 v[118:121], v[130:133], v[202:205], v[118:121]
	v_mfma_f32_16x16x32_bf16 v[110:113], v[170:173], v[202:205], v[110:113]
	v_mfma_f32_16x16x32_bf16 v[102:105], v[130:133], v[210:213], v[102:105]
	v_mfma_f32_16x16x32_bf16 v[94:97], v[170:173], v[210:213], v[94:97]
	v_mfma_f32_16x16x32_bf16 v[86:89], v[130:133], v[218:221], v[86:89]
	v_mfma_f32_16x16x32_bf16 v[78:81], v[170:173], v[218:221], v[78:81]
	v_mfma_f32_16x16x32_bf16 v[126:129], v[134:137], v[198:201], v[126:129]
	v_mfma_f32_16x16x32_bf16 v[122:125], v[174:177], v[198:201], v[122:125]
	v_mfma_f32_16x16x32_bf16 v[118:121], v[134:137], v[206:209], v[118:121]
	v_mfma_f32_16x16x32_bf16 v[110:113], v[174:177], v[206:209], v[110:113]
	v_mfma_f32_16x16x32_bf16 v[102:105], v[134:137], v[214:217], v[102:105]
	v_mfma_f32_16x16x32_bf16 v[94:97], v[174:177], v[214:217], v[94:97]
	v_mfma_f32_16x16x32_bf16 v[86:89], v[134:137], v[222:225], v[86:89]
	v_mfma_f32_16x16x32_bf16 v[78:81], v[174:177], v[222:225], v[78:81]
	s_setprio 0
	s_setprio 1
	v_mfma_f32_16x16x32_bf16 v[114:117], v[178:181], v[194:197], v[114:117]
	v_mfma_f32_16x16x32_bf16 v[106:109], v[186:189], v[194:197], v[106:109]
	v_mfma_f32_16x16x32_bf16 v[98:101], v[178:181], v[202:205], v[98:101]
	v_mfma_f32_16x16x32_bf16 v[90:93], v[186:189], v[202:205], v[90:93]
	v_mfma_f32_16x16x32_bf16 v[82:85], v[178:181], v[210:213], v[82:85]
	v_mfma_f32_16x16x32_bf16 v[74:77], v[186:189], v[210:213], v[74:77]
	v_mfma_f32_16x16x32_bf16 v[70:73], v[178:181], v[218:221], v[70:73]
	v_mfma_f32_16x16x32_bf16 v[66:69], v[186:189], v[218:221], v[66:69]
	v_mfma_f32_16x16x32_bf16 v[114:117], v[182:185], v[198:201], v[114:117]
	v_mfma_f32_16x16x32_bf16 v[106:109], v[190:193], v[198:201], v[106:109]
	v_mfma_f32_16x16x32_bf16 v[98:101], v[182:185], v[206:209], v[98:101]
	v_mfma_f32_16x16x32_bf16 v[90:93], v[190:193], v[206:209], v[90:93]
	v_mfma_f32_16x16x32_bf16 v[82:85], v[182:185], v[214:217], v[82:85]
	v_mfma_f32_16x16x32_bf16 v[74:77], v[190:193], v[214:217], v[74:77]
	v_mfma_f32_16x16x32_bf16 v[70:73], v[182:185], v[222:225], v[70:73]
	v_mfma_f32_16x16x32_bf16 v[66:69], v[190:193], v[222:225], v[66:69]
	s_setprio 0
	s_barrier
	s_add_i32 s75, s67, s55
	v_lshl_add_u64 v[154:155], s[50:51], 0, v[140:141]
	s_mov_b32 m0, s75
	ds_read_b128 v[194:197], v165 offset:16384
	ds_read_b128 v[198:201], v165 offset:17408
	ds_read_b128 v[202:205], v165 offset:18432
	ds_read_b128 v[206:209], v165 offset:19456
	ds_read_b128 v[210:213], v165 offset:20480
	ds_read_b128 v[214:217], v165 offset:21504
	ds_read_b128 v[218:221], v165 offset:22528
	ds_read_b128 v[222:225], v165 offset:23552
	global_load_lds_dwordx4 v[154:155], off
	s_add_i32 m0, s75, 0x2000
	s_add_u32 s76, s50, 0x80000
	v_lshl_add_u64 v[166:167], s[50:51], 0, v[144:145]
	s_addc_u32 s77, s51, 0
	s_add_i32 s75, s68, s55
	global_load_lds_dwordx4 v[166:167], off
	v_lshl_add_u64 v[226:227], s[76:77], 0, v[140:141]
	s_mov_b32 m0, s75
	v_lshl_add_u64 v[228:229], s[52:53], 0, v[142:143]
	global_load_lds_dwordx4 v[226:227], off
	v_lshl_add_u64 v[226:227], s[76:77], 0, v[144:145]
	s_add_i32 m0, s75, 0x2000
	s_nop 0
	global_load_lds_dwordx4 v[226:227], off
	v_lshl_add_u64 v[226:227], s[52:53], 0, v[138:139]
	s_mov_b32 m0, s56
	s_nop 0
	global_load_lds_dwordx4 v[226:227], off
	s_mov_b32 m0, s57
	s_nop 0
	global_load_lds_dwordx4 v[228:229], off
	s_cmp_lg_u32 s32, 0
	s_cbranch_scc1 .Lkw_P1_2
	s_waitcnt vmcnt(8)
.Lkw_P1_2:
	s_mov_b32 s32, 0
	s_waitcnt lgkmcnt(0)
	s_barrier
	s_setprio 1
	s_waitcnt lgkmcnt(0)
	v_mfma_f32_16x16x32_bf16 v[62:65], v[130:133], v[194:197], v[62:65]
	v_mfma_f32_16x16x32_bf16 v[58:61], v[170:173], v[194:197], v[58:61]
	v_mfma_f32_16x16x32_bf16 v[54:57], v[130:133], v[202:205], v[54:57]
	v_mfma_f32_16x16x32_bf16 v[46:49], v[170:173], v[202:205], v[46:49]
	v_mfma_f32_16x16x32_bf16 v[38:41], v[130:133], v[210:213], v[38:41]
	v_mfma_f32_16x16x32_bf16 v[30:33], v[170:173], v[210:213], v[30:33]
	v_mfma_f32_16x16x32_bf16 v[22:25], v[130:133], v[218:221], v[22:25]
	v_mfma_f32_16x16x32_bf16 v[14:17], v[170:173], v[218:221], v[14:17]
	v_mfma_f32_16x16x32_bf16 v[62:65], v[134:137], v[198:201], v[62:65]
	v_mfma_f32_16x16x32_bf16 v[58:61], v[174:177], v[198:201], v[58:61]
	v_mfma_f32_16x16x32_bf16 v[54:57], v[134:137], v[206:209], v[54:57]
	v_mfma_f32_16x16x32_bf16 v[46:49], v[174:177], v[206:209], v[46:49]
	v_mfma_f32_16x16x32_bf16 v[38:41], v[134:137], v[214:217], v[38:41]
	v_mfma_f32_16x16x32_bf16 v[30:33], v[174:177], v[214:217], v[30:33]
	v_mfma_f32_16x16x32_bf16 v[22:25], v[134:137], v[222:225], v[22:25]
	v_mfma_f32_16x16x32_bf16 v[14:17], v[174:177], v[222:225], v[14:17]
	s_setprio 0
	s_setprio 1
	v_mfma_f32_16x16x32_bf16 v[50:53], v[178:181], v[194:197], v[50:53]
	v_mfma_f32_16x16x32_bf16 v[42:45], v[186:189], v[194:197], v[42:45]
	v_mfma_f32_16x16x32_bf16 v[34:37], v[178:181], v[202:205], v[34:37]
	v_mfma_f32_16x16x32_bf16 v[26:29], v[186:189], v[202:205], v[26:29]
	v_mfma_f32_16x16x32_bf16 v[18:21], v[178:181], v[210:213], v[18:21]
	v_mfma_f32_16x16x32_bf16 v[10:13], v[186:189], v[210:213], v[10:13]
	v_mfma_f32_16x16x32_bf16 v[6:9], v[178:181], v[218:221], v[6:9]
	v_mfma_f32_16x16x32_bf16 v[2:5], v[186:189], v[218:221], v[2:5]
	v_mfma_f32_16x16x32_bf16 v[50:53], v[182:185], v[198:201], v[50:53]
	v_mfma_f32_16x16x32_bf16 v[42:45], v[190:193], v[198:201], v[42:45]
	v_mfma_f32_16x16x32_bf16 v[34:37], v[182:185], v[206:209], v[34:37]
	v_mfma_f32_16x16x32_bf16 v[26:29], v[190:193], v[206:209], v[26:29]
	v_mfma_f32_16x16x32_bf16 v[18:21], v[182:185], v[214:217], v[18:21]
	v_mfma_f32_16x16x32_bf16 v[10:13], v[190:193], v[214:217], v[10:13]
	v_mfma_f32_16x16x32_bf16 v[6:9], v[182:185], v[222:225], v[6:9]
	v_mfma_f32_16x16x32_bf16 v[2:5], v[190:193], v[222:225], v[2:5]
	s_setprio 0
	s_barrier
	s_add_i32 s75, 0, 0x18000
	v_add_u32_e32 v156, s75, v159
	s_add_i32 s76, 0, 0x1c000
	ds_read_b128 v[130:133], v156
	ds_read_b128 v[134:137], v156 offset:1024
	ds_read_b128 v[170:173], v156 offset:2048
	ds_read_b128 v[174:177], v156 offset:3072
	v_add_u32_e32 v156, s76, v159
	ds_read_b128 v[178:181], v156
	ds_read_b128 v[182:185], v156 offset:1024
	ds_read_b128 v[186:189], v156 offset:2048
	ds_read_b128 v[190:193], v156 offset:3072
	s_add_u32 s52, s52, 0x80000
	s_addc_u32 s53, s53, 0
	s_mov_b32 m0, s58
	v_lshl_add_u64 v[230:231], s[52:53], 0, v[138:139]
	ds_read_b128 v[194:197], v165 offset:32768
	ds_read_b128 v[198:201], v165 offset:33792
	ds_read_b128 v[202:205], v165 offset:34816
	ds_read_b128 v[206:209], v165 offset:35840
	ds_read_b128 v[210:213], v165 offset:36864
	ds_read_b128 v[214:217], v165 offset:37888
	ds_read_b128 v[218:221], v165 offset:38912
	ds_read_b128 v[222:225], v165 offset:39936
	global_load_lds_dwordx4 v[230:231], off
	v_lshl_add_u64 v[230:231], s[52:53], 0, v[142:143]
	s_mov_b32 m0, s59
	s_nop 0
	global_load_lds_dwordx4 v[230:231], off
	s_waitcnt vmcnt(8)
	s_waitcnt lgkmcnt(0)
	s_barrier
	s_setprio 1
	s_waitcnt lgkmcnt(0)
	v_mfma_f32_16x16x32_bf16 v[126:129], v[130:133], v[194:197], v[126:129]
	v_mfma_f32_16x16x32_bf16 v[122:125], v[170:173], v[194:197], v[122:125]
	v_mfma_f32_16x16x32_bf16 v[118:121], v[130:133], v[202:205], v[118:121]
	v_mfma_f32_16x16x32_bf16 v[110:113], v[170:173], v[202:205], v[110:113]
	v_mfma_f32_16x16x32_bf16 v[102:105], v[130:133], v[210:213], v[102:105]
	v_mfma_f32_16x16x32_bf16 v[94:97], v[170:173], v[210:213], v[94:97]
	v_mfma_f32_16x16x32_bf16 v[86:89], v[130:133], v[218:221], v[86:89]
	v_mfma_f32_16x16x32_bf16 v[78:81], v[170:173], v[218:221], v[78:81]
	v_mfma_f32_16x16x32_bf16 v[126:129], v[134:137], v[198:201], v[126:129]
	v_mfma_f32_16x16x32_bf16 v[122:125], v[174:177], v[198:201], v[122:125]
	v_mfma_f32_16x16x32_bf16 v[118:121], v[134:137], v[206:209], v[118:121]
	v_mfma_f32_16x16x32_bf16 v[110:113], v[174:177], v[206:209], v[110:113]
	v_mfma_f32_16x16x32_bf16 v[102:105], v[134:137], v[214:217], v[102:105]
	v_mfma_f32_16x16x32_bf16 v[94:97], v[174:177], v[214:217], v[94:97]
	v_mfma_f32_16x16x32_bf16 v[86:89], v[134:137], v[222:225], v[86:89]
	v_mfma_f32_16x16x32_bf16 v[78:81], v[174:177], v[222:225], v[78:81]
	s_setprio 0
	s_setprio 1
	v_mfma_f32_16x16x32_bf16 v[114:117], v[178:181], v[194:197], v[114:117]
	v_mfma_f32_16x16x32_bf16 v[106:109], v[186:189], v[194:197], v[106:109]
	v_mfma_f32_16x16x32_bf16 v[98:101], v[178:181], v[202:205], v[98:101]
	v_mfma_f32_16x16x32_bf16 v[90:93], v[186:189], v[202:205], v[90:93]
	v_mfma_f32_16x16x32_bf16 v[82:85], v[178:181], v[210:213], v[82:85]
	v_mfma_f32_16x16x32_bf16 v[74:77], v[186:189], v[210:213], v[74:77]
	v_mfma_f32_16x16x32_bf16 v[70:73], v[178:181], v[218:221], v[70:73]
	v_mfma_f32_16x16x32_bf16 v[66:69], v[186:189], v[218:221], v[66:69]
	v_mfma_f32_16x16x32_bf16 v[114:117], v[182:185], v[198:201], v[114:117]
	v_mfma_f32_16x16x32_bf16 v[106:109], v[190:193], v[198:201], v[106:109]
	v_mfma_f32_16x16x32_bf16 v[98:101], v[182:185], v[206:209], v[98:101]
	v_mfma_f32_16x16x32_bf16 v[90:93], v[190:193], v[206:209], v[90:93]
	v_mfma_f32_16x16x32_bf16 v[82:85], v[182:185], v[214:217], v[82:85]
	v_mfma_f32_16x16x32_bf16 v[74:77], v[190:193], v[214:217], v[74:77]
	v_mfma_f32_16x16x32_bf16 v[70:73], v[182:185], v[222:225], v[70:73]
	v_mfma_f32_16x16x32_bf16 v[66:69], v[190:193], v[222:225], v[66:69]
	s_setprio 0
	s_barrier
	s_add_i32 s52, s75, s55
	v_lshl_add_u64 v[154:155], v[154:155], 0, s[12:13]
	s_mov_b32 m0, s52
	ds_read_b128 v[194:197], v165 offset:49152
	ds_read_b128 v[198:201], v165 offset:50176
	ds_read_b128 v[202:205], v165 offset:51200
	ds_read_b128 v[206:209], v165 offset:52224
	ds_read_b128 v[210:213], v165 offset:53248
	ds_read_b128 v[214:217], v165 offset:54272
	ds_read_b128 v[218:221], v165 offset:55296
	ds_read_b128 v[222:225], v165 offset:56320
	global_load_lds_dwordx4 v[154:155], off
	s_add_i32 m0, s52, 0x2000
	s_add_u32 s50, s50, 0x80080
	v_lshl_add_u64 v[154:155], v[166:167], 0, s[12:13]
	s_addc_u32 s51, s51, 0
	s_add_i32 s52, s76, s55
	global_load_lds_dwordx4 v[154:155], off
	v_lshl_add_u64 v[154:155], s[50:51], 0, v[140:141]
	s_mov_b32 m0, s52
	s_nop 0
	global_load_lds_dwordx4 v[154:155], off
	v_lshl_add_u64 v[154:155], s[50:51], 0, v[144:145]
	s_add_i32 m0, s52, 0x2000
	s_nop 0
	global_load_lds_dwordx4 v[154:155], off
	v_lshl_add_u64 v[154:155], v[226:227], 0, s[12:13]
	s_mov_b32 m0, s64
	s_nop 0
	global_load_lds_dwordx4 v[154:155], off
	v_lshl_add_u64 v[154:155], v[228:229], 0, s[12:13]
	s_mov_b32 m0, s65
	s_nop 0
	global_load_lds_dwordx4 v[154:155], off
	s_waitcnt vmcnt(8)
	s_waitcnt lgkmcnt(0)
	s_barrier
	s_setprio 1
	s_waitcnt lgkmcnt(0)
	v_mfma_f32_16x16x32_bf16 v[62:65], v[130:133], v[194:197], v[62:65]
	v_mfma_f32_16x16x32_bf16 v[58:61], v[170:173], v[194:197], v[58:61]
	v_mfma_f32_16x16x32_bf16 v[54:57], v[130:133], v[202:205], v[54:57]
	v_mfma_f32_16x16x32_bf16 v[46:49], v[170:173], v[202:205], v[46:49]
	v_mfma_f32_16x16x32_bf16 v[38:41], v[130:133], v[210:213], v[38:41]
	v_mfma_f32_16x16x32_bf16 v[30:33], v[170:173], v[210:213], v[30:33]
	v_mfma_f32_16x16x32_bf16 v[22:25], v[130:133], v[218:221], v[22:25]
	v_mfma_f32_16x16x32_bf16 v[14:17], v[170:173], v[218:221], v[14:17]
	v_mfma_f32_16x16x32_bf16 v[62:65], v[134:137], v[198:201], v[62:65]
	v_mfma_f32_16x16x32_bf16 v[58:61], v[174:177], v[198:201], v[58:61]
	v_mfma_f32_16x16x32_bf16 v[54:57], v[134:137], v[206:209], v[54:57]
	v_mfma_f32_16x16x32_bf16 v[46:49], v[174:177], v[206:209], v[46:49]
	v_mfma_f32_16x16x32_bf16 v[38:41], v[134:137], v[214:217], v[38:41]
	v_mfma_f32_16x16x32_bf16 v[30:33], v[174:177], v[214:217], v[30:33]
	v_mfma_f32_16x16x32_bf16 v[22:25], v[134:137], v[222:225], v[22:25]
	v_mfma_f32_16x16x32_bf16 v[14:17], v[174:177], v[222:225], v[14:17]
	s_setprio 0
	s_setprio 1
	v_mfma_f32_16x16x32_bf16 v[50:53], v[178:181], v[194:197], v[50:53]
	v_mfma_f32_16x16x32_bf16 v[42:45], v[186:189], v[194:197], v[42:45]
	v_mfma_f32_16x16x32_bf16 v[34:37], v[178:181], v[202:205], v[34:37]
	v_mfma_f32_16x16x32_bf16 v[26:29], v[186:189], v[202:205], v[26:29]
	v_mfma_f32_16x16x32_bf16 v[18:21], v[178:181], v[210:213], v[18:21]
	v_mfma_f32_16x16x32_bf16 v[10:13], v[186:189], v[210:213], v[10:13]
	v_mfma_f32_16x16x32_bf16 v[6:9], v[178:181], v[218:221], v[6:9]
	v_mfma_f32_16x16x32_bf16 v[2:5], v[186:189], v[218:221], v[2:5]
	v_mfma_f32_16x16x32_bf16 v[50:53], v[182:185], v[198:201], v[50:53]
	v_mfma_f32_16x16x32_bf16 v[42:45], v[190:193], v[198:201], v[42:45]
	v_mfma_f32_16x16x32_bf16 v[34:37], v[182:185], v[206:209], v[34:37]
	v_mfma_f32_16x16x32_bf16 v[26:29], v[190:193], v[206:209], v[26:29]
	v_mfma_f32_16x16x32_bf16 v[18:21], v[182:185], v[214:217], v[18:21]
	v_mfma_f32_16x16x32_bf16 v[10:13], v[190:193], v[214:217], v[10:13]
	v_mfma_f32_16x16x32_bf16 v[6:9], v[182:185], v[222:225], v[6:9]
	v_mfma_f32_16x16x32_bf16 v[2:5], v[190:193], v[222:225], v[2:5]
	s_setprio 0
	s_barrier
	s_add_i32 s74, s74, 2
	s_add_u32 s48, s48, 0x100
	s_addc_u32 s49, s49, 0
	s_add_u32 s72, s72, 0x100
	s_addc_u32 s73, s73, 0
	s_cmp_gt_u32 s74, 29
	s_cbranch_scc0 .LBB0_117
	s_mov_b32 s32, 1
	s_and_b64 vcc, exec, s[28:29]
	s_cbranch_vccz .LBB0_120
	s_barrier

.LBB0_1835:
	v_readlane_b32 s2, v254, 5
	v_readlane_b32 s3, v254, 6
	s_cmp_lt_i32 s2, 6
	s_cselect_b64 s[2:3], -1, 0
	s_and_b64 s[2:3], s[2:3], s[0:1]
	s_andn2_b64 vcc, exec, s[2:3]
	s_cbranch_vccnz .LBB0_1878
	s_mov_b32 s32, 0
	s_waitcnt vmcnt(5)
	v_mov_b32_e32 v10, v0
	s_cmpk_lt_i32 s86, 0x200
	s_cselect_b64 s[0:1], -1, 0
	s_cmpk_gt_i32 s86, 0x1ff
	v_readfirstlane_b32 s14, v10
	s_cbranch_scc1 .LBB0_1842
	s_ashr_i32 s4, s86, 31
	s_lshr_b32 s4, s4, 29
	s_add_i32 s6, s86, s4
	s_and_b32 s4, s6, -8
	s_sub_i32 s7, s86, s4
	s_cmp_gt_i32 s7, -1
	s_cbranch_scc0 .LBB0_1839
	s_lshl_b32 s8, s7, 6
	s_cbranch_execz .LBB0_1840
	s_branch .LBB0_1841

.LBB0_1855:
	ds_read_b128 v[142:145], v148
	ds_read_b128 v[152:155], v148 offset:1024
	ds_read_b128 v[156:159], v148 offset:2048
	ds_read_b128 v[160:163], v148 offset:3072
	ds_read_b128 v[164:167], v149
	ds_read_b128 v[168:171], v149 offset:1024
	ds_read_b128 v[172:175], v149 offset:2048
	ds_read_b128 v[176:179], v149 offset:3072
	s_add_u32 s26, s24, 0x100
	s_addc_u32 s27, s25, 0
	s_cmp_eq_u32 s55, 60
	s_cselect_b32 s31, s19, s27
	s_cselect_b32 s30, s51, s26
	s_cselect_b32 s29, s17, s54
	s_cselect_b32 s28, s52, s53
	v_lshl_add_u64 v[212:213], s[24:25], 0, v[134:135]
	s_add_i32 m0, s5, 0xc000
	ds_read_b128 v[180:183], v150
	ds_read_b128 v[184:187], v150 offset:1024
	ds_read_b128 v[188:191], v150 offset:2048
	ds_read_b128 v[192:195], v150 offset:3072
	ds_read_b128 v[196:199], v150 offset:4096
	ds_read_b128 v[200:203], v150 offset:5120
	ds_read_b128 v[204:207], v150 offset:6144
	ds_read_b128 v[208:211], v150 offset:7168
	global_load_lds_dwordx4 v[212:213], off
	v_lshl_add_u64 v[212:213], s[24:25], 0, v[136:137]
	s_add_i32 m0, s5, 0xe000
	s_nop 0
	global_load_lds_dwordx4 v[212:213], off
	s_cmp_lg_u32 s32, 0
	s_cbranch_scc1 .Lkw_P5_1
	s_waitcnt vmcnt(8)
.Lkw_P5_1:
	s_waitcnt lgkmcnt(0)
	s_barrier
	s_setprio 1
	s_waitcnt lgkmcnt(0)
	v_mfma_f32_16x16x32_bf16 v[126:129], v[142:145], v[180:183], v[126:129]
	v_mfma_f32_16x16x32_bf16 v[122:125], v[156:159], v[180:183], v[122:125]
	v_mfma_f32_16x16x32_bf16 v[110:113], v[142:145], v[188:191], v[110:113]
	v_mfma_f32_16x16x32_bf16 v[106:109], v[156:159], v[188:191], v[106:109]
	v_mfma_f32_16x16x32_bf16 v[94:97], v[142:145], v[196:199], v[94:97]
	v_mfma_f32_16x16x32_bf16 v[90:93], v[156:159], v[196:199], v[90:93]
	v_mfma_f32_16x16x32_bf16 v[78:81], v[142:145], v[204:207], v[78:81]
	v_mfma_f32_16x16x32_bf16 v[74:77], v[156:159], v[204:207], v[74:77]
	v_mfma_f32_16x16x32_bf16 v[126:129], v[152:155], v[184:187], v[126:129]
	v_mfma_f32_16x16x32_bf16 v[122:125], v[160:163], v[184:187], v[122:125]
	v_mfma_f32_16x16x32_bf16 v[110:113], v[152:155], v[192:195], v[110:113]
	v_mfma_f32_16x16x32_bf16 v[106:109], v[160:163], v[192:195], v[106:109]
	v_mfma_f32_16x16x32_bf16 v[94:97], v[152:155], v[200:203], v[94:97]
	v_mfma_f32_16x16x32_bf16 v[90:93], v[160:163], v[200:203], v[90:93]
	v_mfma_f32_16x16x32_bf16 v[78:81], v[152:155], v[208:211], v[78:81]
	v_mfma_f32_16x16x32_bf16 v[74:77], v[160:163], v[208:211], v[74:77]
	s_setprio 0
	s_setprio 1
	v_mfma_f32_16x16x32_bf16 v[118:121], v[164:167], v[180:183], v[118:121]
	v_mfma_f32_16x16x32_bf16 v[114:117], v[172:175], v[180:183], v[114:117]
	v_mfma_f32_16x16x32_bf16 v[102:105], v[164:167], v[188:191], v[102:105]
	v_mfma_f32_16x16x32_bf16 v[98:101], v[172:175], v[188:191], v[98:101]
	v_mfma_f32_16x16x32_bf16 v[86:89], v[164:167], v[196:199], v[86:89]
	v_mfma_f32_16x16x32_bf16 v[82:85], v[172:175], v[196:199], v[82:85]
	v_mfma_f32_16x16x32_bf16 v[70:73], v[164:167], v[204:207], v[70:73]
	v_mfma_f32_16x16x32_bf16 v[66:69], v[172:175], v[204:207], v[66:69]
	v_mfma_f32_16x16x32_bf16 v[118:121], v[168:171], v[184:187], v[118:121]
	v_mfma_f32_16x16x32_bf16 v[114:117], v[176:179], v[184:187], v[114:117]
	v_mfma_f32_16x16x32_bf16 v[102:105], v[168:171], v[192:195], v[102:105]
	v_mfma_f32_16x16x32_bf16 v[98:101], v[176:179], v[192:195], v[98:101]
	v_mfma_f32_16x16x32_bf16 v[86:89], v[168:171], v[200:203], v[86:89]
	v_mfma_f32_16x16x32_bf16 v[82:85], v[176:179], v[200:203], v[82:85]
	v_mfma_f32_16x16x32_bf16 v[70:73], v[168:171], v[208:211], v[70:73]
	v_mfma_f32_16x16x32_bf16 v[66:69], v[176:179], v[208:211], v[66:69]
	s_setprio 0
	s_barrier
	s_add_i32 s24, s48, s37
	v_lshl_add_u64 v[212:213], s[28:29], 0, v[130:131]
	s_mov_b32 m0, s24
	ds_read_b128 v[180:183], v150 offset:16384
	ds_read_b128 v[184:187], v150 offset:17408
	ds_read_b128 v[188:191], v150 offset:18432
	ds_read_b128 v[192:195], v150 offset:19456
	ds_read_b128 v[196:199], v150 offset:20480
	ds_read_b128 v[200:203], v150 offset:21504
	ds_read_b128 v[204:207], v150 offset:22528
	ds_read_b128 v[208:211], v150 offset:23552
	global_load_lds_dwordx4 v[212:213], off
	s_add_i32 m0, s24, 0x2000
	s_add_u32 s24, s28, 0x100000
	v_lshl_add_u64 v[214:215], s[28:29], 0, v[132:133]
	s_addc_u32 s25, s29, 0
	s_add_i32 s56, s49, s37
	global_load_lds_dwordx4 v[214:215], off
	v_lshl_add_u64 v[216:217], s[24:25], 0, v[130:131]
	s_mov_b32 m0, s56
	v_lshl_add_u64 v[218:219], s[30:31], 0, v[132:133]
	global_load_lds_dwordx4 v[216:217], off
	v_lshl_add_u64 v[216:217], s[24:25], 0, v[132:133]
	s_add_i32 m0, s56, 0x2000
	s_nop 0
	global_load_lds_dwordx4 v[216:217], off
	v_lshl_add_u64 v[216:217], s[30:31], 0, v[130:131]
	s_mov_b32 m0, s5
	s_nop 0
	global_load_lds_dwordx4 v[216:217], off
	s_mov_b32 m0, s38
	s_nop 0
	global_load_lds_dwordx4 v[218:219], off
	s_cmp_lg_u32 s32, 0
	s_cbranch_scc1 .Lkw_P5_2
	s_waitcnt vmcnt(8)
.Lkw_P5_2:
	s_mov_b32 s32, 0
	s_waitcnt lgkmcnt(0)
	s_barrier
	s_setprio 1
	s_waitcnt lgkmcnt(0)
	v_mfma_f32_16x16x32_bf16 v[62:65], v[142:145], v[180:183], v[62:65]
	v_mfma_f32_16x16x32_bf16 v[58:61], v[156:159], v[180:183], v[58:61]
	v_mfma_f32_16x16x32_bf16 v[46:49], v[142:145], v[188:191], v[46:49]
	v_mfma_f32_16x16x32_bf16 v[42:45], v[156:159], v[188:191], v[42:45]
	v_mfma_f32_16x16x32_bf16 v[30:33], v[142:145], v[196:199], v[30:33]
	v_mfma_f32_16x16x32_bf16 v[26:29], v[156:159], v[196:199], v[26:29]
	v_mfma_f32_16x16x32_bf16 v[14:17], v[142:145], v[204:207], v[14:17]
	v_mfma_f32_16x16x32_bf16 v[10:13], v[156:159], v[204:207], v[10:13]
	v_mfma_f32_16x16x32_bf16 v[62:65], v[152:155], v[184:187], v[62:65]
	v_mfma_f32_16x16x32_bf16 v[58:61], v[160:163], v[184:187], v[58:61]
	v_mfma_f32_16x16x32_bf16 v[46:49], v[152:155], v[192:195], v[46:49]
	v_mfma_f32_16x16x32_bf16 v[42:45], v[160:163], v[192:195], v[42:45]
	v_mfma_f32_16x16x32_bf16 v[30:33], v[152:155], v[200:203], v[30:33]
	v_mfma_f32_16x16x32_bf16 v[26:29], v[160:163], v[200:203], v[26:29]
	v_mfma_f32_16x16x32_bf16 v[14:17], v[152:155], v[208:211], v[14:17]
	v_mfma_f32_16x16x32_bf16 v[10:13], v[160:163], v[208:211], v[10:13]
	s_setprio 0
	s_setprio 1
	v_mfma_f32_16x16x32_bf16 v[54:57], v[164:167], v[180:183], v[54:57]
	v_mfma_f32_16x16x32_bf16 v[50:53], v[172:175], v[180:183], v[50:53]
	v_mfma_f32_16x16x32_bf16 v[38:41], v[164:167], v[188:191], v[38:41]
	v_mfma_f32_16x16x32_bf16 v[34:37], v[172:175], v[188:191], v[34:37]
	v_mfma_f32_16x16x32_bf16 v[22:25], v[164:167], v[196:199], v[22:25]
	v_mfma_f32_16x16x32_bf16 v[18:21], v[172:175], v[196:199], v[18:21]
	v_mfma_f32_16x16x32_bf16 v[6:9], v[164:167], v[204:207], v[6:9]
	v_mfma_f32_16x16x32_bf16 v[2:5], v[172:175], v[204:207], v[2:5]
	v_mfma_f32_16x16x32_bf16 v[54:57], v[168:171], v[184:187], v[54:57]
	v_mfma_f32_16x16x32_bf16 v[50:53], v[176:179], v[184:187], v[50:53]
	v_mfma_f32_16x16x32_bf16 v[38:41], v[168:171], v[192:195], v[38:41]
	v_mfma_f32_16x16x32_bf16 v[34:37], v[176:179], v[192:195], v[34:37]
	v_mfma_f32_16x16x32_bf16 v[22:25], v[168:171], v[200:203], v[22:25]
	v_mfma_f32_16x16x32_bf16 v[18:21], v[176:179], v[200:203], v[18:21]
	v_mfma_f32_16x16x32_bf16 v[6:9], v[168:171], v[208:211], v[6:9]
	v_mfma_f32_16x16x32_bf16 v[2:5], v[176:179], v[208:211], v[2:5]
	s_setprio 0
	s_barrier
	s_add_i32 s56, 0, 0x18000
	s_add_i32 s57, 0, 0x1c000
	v_add_u32_e32 v160, s56, v147
	v_add_u32_e32 v176, s57, v147
	ds_read_b128 v[142:145], v160
	ds_read_b128 v[152:155], v160 offset:1024
	ds_read_b128 v[156:159], v160 offset:2048
	ds_read_b128 v[160:163], v160 offset:3072
	ds_read_b128 v[164:167], v176
	ds_read_b128 v[168:171], v176 offset:1024
	ds_read_b128 v[172:175], v176 offset:2048
	ds_read_b128 v[176:179], v176 offset:3072
	s_add_u32 s24, s30, 0x100000
	s_addc_u32 s25, s31, 0
	s_mov_b32 m0, s39
	v_lshl_add_u64 v[220:221], s[24:25], 0, v[130:131]
	ds_read_b128 v[180:183], v150 offset:32768
	ds_read_b128 v[184:187], v150 offset:33792
	ds_read_b128 v[188:191], v150 offset:34816
	ds_read_b128 v[192:195], v150 offset:35840
	ds_read_b128 v[196:199], v150 offset:36864
	ds_read_b128 v[200:203], v150 offset:37888
	ds_read_b128 v[204:207], v150 offset:38912
	ds_read_b128 v[208:211], v150 offset:39936
	global_load_lds_dwordx4 v[220:221], off
	v_lshl_add_u64 v[220:221], s[24:25], 0, v[132:133]
	s_mov_b32 m0, s40
	s_nop 0
	global_load_lds_dwordx4 v[220:221], off
	s_waitcnt vmcnt(8)
	s_waitcnt lgkmcnt(0)
	s_barrier
	s_setprio 1
	s_waitcnt lgkmcnt(0)
	v_mfma_f32_16x16x32_bf16 v[126:129], v[142:145], v[180:183], v[126:129]
	v_mfma_f32_16x16x32_bf16 v[122:125], v[156:159], v[180:183], v[122:125]
	v_mfma_f32_16x16x32_bf16 v[110:113], v[142:145], v[188:191], v[110:113]
	v_mfma_f32_16x16x32_bf16 v[106:109], v[156:159], v[188:191], v[106:109]
	v_mfma_f32_16x16x32_bf16 v[94:97], v[142:145], v[196:199], v[94:97]
	v_mfma_f32_16x16x32_bf16 v[90:93], v[156:159], v[196:199], v[90:93]
	v_mfma_f32_16x16x32_bf16 v[78:81], v[142:145], v[204:207], v[78:81]
	v_mfma_f32_16x16x32_bf16 v[74:77], v[156:159], v[204:207], v[74:77]
	v_mfma_f32_16x16x32_bf16 v[126:129], v[152:155], v[184:187], v[126:129]
	v_mfma_f32_16x16x32_bf16 v[122:125], v[160:163], v[184:187], v[122:125]
	v_mfma_f32_16x16x32_bf16 v[110:113], v[152:155], v[192:195], v[110:113]
	v_mfma_f32_16x16x32_bf16 v[106:109], v[160:163], v[192:195], v[106:109]
	v_mfma_f32_16x16x32_bf16 v[94:97], v[152:155], v[200:203], v[94:97]
	v_mfma_f32_16x16x32_bf16 v[90:93], v[160:163], v[200:203], v[90:93]
	v_mfma_f32_16x16x32_bf16 v[78:81], v[152:155], v[208:211], v[78:81]
	v_mfma_f32_16x16x32_bf16 v[74:77], v[160:163], v[208:211], v[74:77]
	s_setprio 0
	s_setprio 1
	v_mfma_f32_16x16x32_bf16 v[118:121], v[164:167], v[180:183], v[118:121]
	v_mfma_f32_16x16x32_bf16 v[114:117], v[172:175], v[180:183], v[114:117]
	v_mfma_f32_16x16x32_bf16 v[102:105], v[164:167], v[188:191], v[102:105]
	v_mfma_f32_16x16x32_bf16 v[98:101], v[172:175], v[188:191], v[98:101]
	v_mfma_f32_16x16x32_bf16 v[86:89], v[164:167], v[196:199], v[86:89]
	v_mfma_f32_16x16x32_bf16 v[82:85], v[172:175], v[196:199], v[82:85]
	v_mfma_f32_16x16x32_bf16 v[70:73], v[164:167], v[204:207], v[70:73]
	v_mfma_f32_16x16x32_bf16 v[66:69], v[172:175], v[204:207], v[66:69]
	v_mfma_f32_16x16x32_bf16 v[118:121], v[168:171], v[184:187], v[118:121]
	v_mfma_f32_16x16x32_bf16 v[114:117], v[176:179], v[184:187], v[114:117]
	v_mfma_f32_16x16x32_bf16 v[102:105], v[168:171], v[192:195], v[102:105]
	v_mfma_f32_16x16x32_bf16 v[98:101], v[176:179], v[192:195], v[98:101]
	v_mfma_f32_16x16x32_bf16 v[86:89], v[168:171], v[200:203], v[86:89]
	v_mfma_f32_16x16x32_bf16 v[82:85], v[176:179], v[200:203], v[82:85]
	v_mfma_f32_16x16x32_bf16 v[70:73], v[168:171], v[208:211], v[70:73]
	v_mfma_f32_16x16x32_bf16 v[66:69], v[176:179], v[208:211], v[66:69]
	s_setprio 0
	s_barrier
	s_add_i32 s24, s56, s37
	v_lshl_add_u64 v[212:213], v[212:213], 0, s[12:13]
	s_mov_b32 m0, s24
	ds_read_b128 v[180:183], v150 offset:49152
	ds_read_b128 v[184:187], v150 offset:50176
	ds_read_b128 v[188:191], v150 offset:51200
	ds_read_b128 v[192:195], v150 offset:52224
	ds_read_b128 v[196:199], v150 offset:53248
	ds_read_b128 v[200:203], v150 offset:54272
	ds_read_b128 v[204:207], v150 offset:55296
	ds_read_b128 v[208:211], v150 offset:56320
	global_load_lds_dwordx4 v[212:213], off
	s_add_i32 m0, s24, 0x2000
	s_add_u32 s24, s28, 0x100080
	v_lshl_add_u64 v[212:213], v[214:215], 0, s[12:13]
	s_addc_u32 s25, s29, 0
	s_add_i32 s28, s57, s37
	global_load_lds_dwordx4 v[212:213], off
	v_lshl_add_u64 v[212:213], s[24:25], 0, v[130:131]
	s_mov_b32 m0, s28
	s_nop 0
	global_load_lds_dwordx4 v[212:213], off
	v_lshl_add_u64 v[212:213], s[24:25], 0, v[132:133]
	s_add_i32 m0, s28, 0x2000
	s_nop 0
	global_load_lds_dwordx4 v[212:213], off
	v_lshl_add_u64 v[212:213], v[216:217], 0, s[12:13]
	s_mov_b32 m0, s44
	s_nop 0
	global_load_lds_dwordx4 v[212:213], off
	v_lshl_add_u64 v[212:213], v[218:219], 0, s[12:13]
	s_mov_b32 m0, s45
	s_nop 0
	global_load_lds_dwordx4 v[212:213], off
	s_waitcnt vmcnt(8)
	s_waitcnt lgkmcnt(0)
	s_barrier
	s_setprio 1
	s_waitcnt lgkmcnt(0)
	v_mfma_f32_16x16x32_bf16 v[62:65], v[142:145], v[180:183], v[62:65]
	v_mfma_f32_16x16x32_bf16 v[58:61], v[156:159], v[180:183], v[58:61]
	v_mfma_f32_16x16x32_bf16 v[46:49], v[142:145], v[188:191], v[46:49]
	v_mfma_f32_16x16x32_bf16 v[42:45], v[156:159], v[188:191], v[42:45]
	v_mfma_f32_16x16x32_bf16 v[30:33], v[142:145], v[196:199], v[30:33]
	v_mfma_f32_16x16x32_bf16 v[26:29], v[156:159], v[196:199], v[26:29]
	v_mfma_f32_16x16x32_bf16 v[14:17], v[142:145], v[204:207], v[14:17]
	v_mfma_f32_16x16x32_bf16 v[10:13], v[156:159], v[204:207], v[10:13]
	v_mfma_f32_16x16x32_bf16 v[62:65], v[152:155], v[184:187], v[62:65]
	v_mfma_f32_16x16x32_bf16 v[58:61], v[160:163], v[184:187], v[58:61]
	v_mfma_f32_16x16x32_bf16 v[46:49], v[152:155], v[192:195], v[46:49]
	v_mfma_f32_16x16x32_bf16 v[42:45], v[160:163], v[192:195], v[42:45]
	v_mfma_f32_16x16x32_bf16 v[30:33], v[152:155], v[200:203], v[30:33]
	v_mfma_f32_16x16x32_bf16 v[26:29], v[160:163], v[200:203], v[26:29]
	v_mfma_f32_16x16x32_bf16 v[14:17], v[152:155], v[208:211], v[14:17]
	v_mfma_f32_16x16x32_bf16 v[10:13], v[160:163], v[208:211], v[10:13]
	s_setprio 0
	s_setprio 1
	v_mfma_f32_16x16x32_bf16 v[54:57], v[164:167], v[180:183], v[54:57]
	v_mfma_f32_16x16x32_bf16 v[50:53], v[172:175], v[180:183], v[50:53]
	v_mfma_f32_16x16x32_bf16 v[38:41], v[164:167], v[188:191], v[38:41]
	v_mfma_f32_16x16x32_bf16 v[34:37], v[172:175], v[188:191], v[34:37]
	v_mfma_f32_16x16x32_bf16 v[22:25], v[164:167], v[196:199], v[22:25]
	v_mfma_f32_16x16x32_bf16 v[18:21], v[172:175], v[196:199], v[18:21]
	v_mfma_f32_16x16x32_bf16 v[6:9], v[164:167], v[204:207], v[6:9]
	v_mfma_f32_16x16x32_bf16 v[2:5], v[172:175], v[204:207], v[2:5]
	v_mfma_f32_16x16x32_bf16 v[54:57], v[168:171], v[184:187], v[54:57]
	v_mfma_f32_16x16x32_bf16 v[50:53], v[176:179], v[184:187], v[50:53]
	v_mfma_f32_16x16x32_bf16 v[38:41], v[168:171], v[192:195], v[38:41]
	v_mfma_f32_16x16x32_bf16 v[34:37], v[176:179], v[192:195], v[34:37]
	v_mfma_f32_16x16x32_bf16 v[22:25], v[168:171], v[200:203], v[22:25]
	v_mfma_f32_16x16x32_bf16 v[18:21], v[176:179], v[200:203], v[18:21]
	v_mfma_f32_16x16x32_bf16 v[6:9], v[168:171], v[208:211], v[6:9]
	v_mfma_f32_16x16x32_bf16 v[2:5], v[176:179], v[208:211], v[2:5]
	s_setprio 0
	s_barrier
	s_add_i32 s55, s55, 2
	s_add_u32 s53, s53, 0x100
	s_addc_u32 s54, s54, 0
	s_cmp_gt_u32 s55, 61
	s_mov_b64 s[24:25], s[26:27]
	s_cbranch_scc0 .LBB0_1855
	s_mov_b32 s32, 1
	s_and_b64 vcc, exec, s[14:15]
	s_cbranch_vccz .LBB0_1858
	s_barrier

.LBB0_1932:
	v_readlane_b32 s2, v254, 5
	v_readlane_b32 s3, v254, 6
	s_cmp_lt_i32 s2, 7
	s_cselect_b64 s[2:3], -1, 0
	s_and_b64 s[2:3], s[2:3], s[0:1]
	s_andn2_b64 vcc, exec, s[2:3]
	s_cbranch_vccnz .LBB0_1951
	s_mov_b32 s32, 0
	s_waitcnt vmcnt(5)
	v_mov_b32_e32 v11, v0
	s_cmpk_gt_i32 s86, 0xaff
	v_readfirstlane_b32 s1, v11
	s_cbranch_scc1 .LBB0_1951
	v_lshlrev_b32_e32 v1, 4, v11
	s_waitcnt vmcnt(0)
	v_add_u32_e32 v2, 0x2000, v1
	s_waitcnt lgkmcnt(0)
	v_ashrrev_i32_e32 v3, 31, v2
	v_lshrrev_b32_e32 v3, 22, v3
	v_add_u32_e32 v3, v2, v3
	v_ashrrev_i32_e32 v10, 10, v3
	v_mul_i32_i24_e32 v3, 0x400, v10
	v_sub_u32_e32 v2, v2, v3
	v_lshrrev_b32_e32 v3, 4, v2
	v_bitop3_b32 v2, v3, v2, 32 bitop3:0x6c
	v_ashrrev_i32_e32 v3, 31, v2
	v_lshrrev_b32_e32 v3, 26, v3
	v_add_u32_e32 v3, v2, v3
	v_lshlrev_b32_e32 v4, 3, v10
	v_ashrrev_i32_e32 v12, 6, v3
	v_and_b32_e32 v4, -16, v4
	v_add_u32_e32 v4, v12, v4
	v_and_b32_e32 v5, 3, v12
	s_mov_b32 s0, 0xfffe0
	v_lshrrev_b32_e32 v6, 2, v4
	v_lshlrev_b32_e32 v7, 1, v4
	v_and_b32_e32 v3, 0xc0, v3
	v_and_or_b32 v5, v4, s0, v5
	v_and_b32_e32 v6, 4, v6
	v_and_b32_e32 v7, 24, v7
	v_sub_u32_e32 v2, v2, v3
	v_mov_b32_e32 v3, 1
	v_or3_b32 v5, v5, v6, v7
	v_lshlrev_b32_e32 v6, 5, v10
	v_ashrrev_i16_sdwa v2, v3, sext(v2) dst_sel:DWORD dst_unused:UNUSED_PAD src0_sel:DWORD src1_sel:BYTE_0
	v_and_b32_e32 v6, 32, v6
	v_bfe_i32 v13, v2, 0, 16
	v_add_lshl_u32 v2, v6, v13, 1
	v_lshl_add_u32 v182, v5, 12, v2
	v_lshl_add_u32 v184, v4, 12, v2
	v_bfe_i32 v2, v11, 27, 1
	v_lshrrev_b32_e32 v2, 22, v2
	v_add_u32_e32 v2, v1, v2
	v_and_b32_e32 v2, 0xfffffc00, v2
	v_sub_u32_e32 v1, v1, v2
	v_lshrrev_b32_e32 v2, 4, v1
	v_ashrrev_i32_e32 v4, 31, v11
	v_bitop3_b32 v1, v2, v1, 32 bitop3:0x6c
	v_lshrrev_b32_e32 v4, 26, v4
	v_ashrrev_i32_e32 v2, 31, v1
	v_add_u32_e32 v4, v11, v4
	v_lshrrev_b32_e32 v2, 26, v2
	v_ashrrev_i32_e32 v15, 6, v4
	v_add_u32_e32 v2, v1, v2
	v_lshlrev_b32_e32 v4, 3, v15
	s_add_u32 s17, s92, 0x6100000
	v_ashrrev_i32_e32 v14, 6, v2
	v_and_b32_e32 v4, -16, v4
	s_addc_u32 s30, s93, 0
	v_add_u32_e32 v4, v14, v4
	v_and_b32_e32 v5, 3, v14
	s_ashr_i32 s33, s86, 31
	v_and_or_b32 v5, v4, s0, v5
	s_lshr_b32 s0, s33, 29
	s_add_i32 s0, s86, s0
	s_ashr_i32 s12, s1, 6
	s_ashr_i32 s4, s0, 3
	s_and_b32 s0, s0, -8
	s_ashr_i32 s13, s1, 8
	s_lshl_b32 s31, s12, 10
	s_sub_i32 s0, s86, s0
	s_cmp_lt_i32 s0, 0
	s_movk_i32 s34, 0x161
	s_cselect_b32 s5, s34, 0x160
	s_mul_i32 s0, s0, s5
	s_add_i32 s0, s0, s4
	s_mul_hi_i32 s4, s0, 0x2e8ba2e9
	s_lshr_b32 s5, s4, 31
	s_ashr_i32 s4, s4, 5
	s_add_i32 s4, s4, s5
	s_lshl_b32 s5, s4, 2
	s_mulk_i32 s4, 0xb0
	s_sub_i32 s4, s0, s4
	s_sext_i32_i16 s0, s4
	s_bfe_u32 s0, s0, 0x2001d
	s_add_i32 s6, s4, s0
	s_sext_i32_i16 s0, s6
	s_and_b32 s6, s6, 0xfffc
	s_sub_i32 s4, s4, s6
	s_sext_i32_i16 s4, s4
	v_lshrrev_b32_e32 v6, 2, v4
	v_lshlrev_b32_e32 v7, 1, v4
	v_and_b32_e32 v2, 0xc0, v2
	s_lshr_b32 s0, s0, 2
	s_add_i32 s6, s5, s4
	v_and_b32_e32 v6, 4, v6
	v_and_b32_e32 v7, 24, v7
	v_sub_u32_e32 v1, v1, v2
	s_ashr_i32 s7, s6, 31
	s_bfe_i64 s[8:9], s[0:1], 0x100000
	v_or3_b32 v5, v5, v6, v7
	v_lshlrev_b32_e32 v6, 5, v15
	v_ashrrev_i16_sdwa v1, v3, sext(v1) dst_sel:DWORD dst_unused:UNUSED_PAD src0_sel:DWORD src1_sel:BYTE_0
	s_lshl_b64 s[4:5], s[6:7], 20
	s_lshl_b64 s[8:9], s[8:9], 20
	v_and_b32_e32 v6, 32, v6
	v_bfe_i32 v16, v1, 0, 16
	s_add_u32 s26, s17, s8
	v_add_lshl_u32 v1, v6, v16, 1
	s_addc_u32 s27, s30, s9
	s_add_i32 s35, s31, 0
	v_lshl_add_u32 v186, v5, 12, v1
	s_add_i32 m0, s35, 0x10000
	v_lshl_add_u32 v188, v4, 12, v1
	global_load_lds_dwordx4 v186, s[26:27]
	s_add_i32 m0, s35, 0x12000
	s_add_u32 s8, s26, 0x80000
	global_load_lds_dwordx4 v182, s[26:27]
	s_addc_u32 s9, s27, 0
	s_add_i32 m0, s35, 0x14000
	v_mov_b32_e32 v187, 0
	global_load_lds_dwordx4 v186, s[8:9]
	s_add_i32 m0, s35, 0x16000
	v_mov_b32_e32 v183, v187
	global_load_lds_dwordx4 v182, s[8:9]
	s_add_u32 s8, s88, s4
	s_addc_u32 s9, s89, s5
	s_add_i32 s36, s35, 0x2000
	s_mov_b32 m0, s35
	s_add_u32 s4, s8, 0x80000
	global_load_lds_dwordx4 v188, s[8:9]
	s_mov_b32 m0, s36
	s_addc_u32 s5, s9, 0
	s_add_i32 s37, s35, 0x4000
	global_load_lds_dwordx4 v184, s[8:9]
	s_mov_b32 m0, s37
	s_add_i32 s38, s35, 0x6000
	global_load_lds_dwordx4 v188, s[4:5]
	s_mov_b32 m0, s38
	v_mov_b32_e32 v189, v187
	global_load_lds_dwordx4 v184, s[4:5]
	v_mov_b32_e32 v185, v187
	s_cmp_eq_u32 s13, 1
	s_mov_b32 s39, 0
	v_lshl_add_u64 v[8:9], s[26:27], 0, v[186:187]
	v_lshl_add_u64 v[4:5], s[26:27], 0, v[182:183]
	v_lshl_add_u64 v[2:3], s[8:9], 0, v[188:189]
	s_cselect_b64 s[4:5], -1, 0
	s_cmp_lg_u32 s13, 1
	v_lshl_add_u64 v[6:7], s[8:9], 0, v[184:185]
	s_cbranch_scc1 .LBB0_1936
	s_barrier

.LBB0_1942:
	ds_read_b128 v[130:133], v200
	s_waitcnt lgkmcnt(0)
	ds_read_b128 v[134:137], v200 offset:1024
	ds_read_b128 v[138:141], v200 offset:2048
	ds_read_b128 v[142:145], v200 offset:3072
	ds_read_b128 v[146:149], v201
	ds_read_b128 v[150:153], v201 offset:1024
	ds_read_b128 v[154:157], v201 offset:2048
	ds_read_b128 v[158:161], v201 offset:3072
	s_add_u32 s26, s8, 0xfff80080
	s_addc_u32 s27, s9, -1
	s_cmp_eq_u32 s53, 28
	s_cselect_b32 s29, s7, s27
	s_cselect_b32 s28, s21, s26
	s_cselect_b32 s27, s19, s52
	s_cselect_b32 s26, s50, s51
	v_lshl_add_u64 v[216:217], s[8:9], 0, v[190:191]
	s_add_i32 m0, s35, 0xc000
	ds_read_b128 v[162:165], v202
	ds_read_b128 v[166:169], v202 offset:1024
	ds_read_b128 v[170:173], v202 offset:2048
	ds_read_b128 v[174:177], v202 offset:3072
	ds_read_b128 v[178:181], v202 offset:4096
	ds_read_b128 v[204:207], v202 offset:5120
	ds_read_b128 v[208:211], v202 offset:6144
	ds_read_b128 v[212:215], v202 offset:7168
	global_load_lds_dwordx4 v[216:217], off
	v_lshl_add_u64 v[216:217], s[8:9], 0, v[192:193]
	s_add_i32 m0, s35, 0xe000
	s_nop 0
	global_load_lds_dwordx4 v[216:217], off
	s_cmp_lg_u32 s32, 0
	s_cbranch_scc1 .Lkw_P6_1
	s_waitcnt vmcnt(8)
.Lkw_P6_1:
	s_waitcnt lgkmcnt(0)
	s_barrier
	s_setprio 1
	s_waitcnt lgkmcnt(0)
	v_mfma_f32_16x16x32_bf16 v[126:129], v[130:133], v[162:165], v[126:129]
	v_mfma_f32_16x16x32_bf16 v[122:125], v[138:141], v[162:165], v[122:125]
	v_mfma_f32_16x16x32_bf16 v[118:121], v[130:133], v[170:173], v[118:121]
	v_mfma_f32_16x16x32_bf16 v[110:113], v[138:141], v[170:173], v[110:113]
	v_mfma_f32_16x16x32_bf16 v[102:105], v[130:133], v[178:181], v[102:105]
	v_mfma_f32_16x16x32_bf16 v[94:97], v[138:141], v[178:181], v[94:97]
	v_mfma_f32_16x16x32_bf16 v[86:89], v[130:133], v[208:211], v[86:89]
	v_mfma_f32_16x16x32_bf16 v[78:81], v[138:141], v[208:211], v[78:81]
	v_mfma_f32_16x16x32_bf16 v[126:129], v[134:137], v[166:169], v[126:129]
	v_mfma_f32_16x16x32_bf16 v[122:125], v[142:145], v[166:169], v[122:125]
	v_mfma_f32_16x16x32_bf16 v[118:121], v[134:137], v[174:177], v[118:121]
	v_mfma_f32_16x16x32_bf16 v[110:113], v[142:145], v[174:177], v[110:113]
	v_mfma_f32_16x16x32_bf16 v[102:105], v[134:137], v[204:207], v[102:105]
	v_mfma_f32_16x16x32_bf16 v[94:97], v[142:145], v[204:207], v[94:97]
	v_mfma_f32_16x16x32_bf16 v[86:89], v[134:137], v[212:215], v[86:89]
	v_mfma_f32_16x16x32_bf16 v[78:81], v[142:145], v[212:215], v[78:81]
	s_setprio 0
	s_setprio 1
	v_mfma_f32_16x16x32_bf16 v[114:117], v[146:149], v[162:165], v[114:117]
	v_mfma_f32_16x16x32_bf16 v[106:109], v[154:157], v[162:165], v[106:109]
	v_mfma_f32_16x16x32_bf16 v[98:101], v[146:149], v[170:173], v[98:101]
	v_mfma_f32_16x16x32_bf16 v[90:93], v[154:157], v[170:173], v[90:93]
	v_mfma_f32_16x16x32_bf16 v[82:85], v[146:149], v[178:181], v[82:85]
	v_mfma_f32_16x16x32_bf16 v[74:77], v[154:157], v[178:181], v[74:77]
	v_mfma_f32_16x16x32_bf16 v[70:73], v[146:149], v[208:211], v[70:73]
	v_mfma_f32_16x16x32_bf16 v[66:69], v[154:157], v[208:211], v[66:69]
	v_mfma_f32_16x16x32_bf16 v[114:117], v[150:153], v[166:169], v[114:117]
	v_mfma_f32_16x16x32_bf16 v[106:109], v[158:161], v[166:169], v[106:109]
	v_mfma_f32_16x16x32_bf16 v[98:101], v[150:153], v[174:177], v[98:101]
	v_mfma_f32_16x16x32_bf16 v[90:93], v[158:161], v[174:177], v[90:93]
	v_mfma_f32_16x16x32_bf16 v[82:85], v[150:153], v[204:207], v[82:85]
	v_mfma_f32_16x16x32_bf16 v[74:77], v[158:161], v[204:207], v[74:77]
	v_mfma_f32_16x16x32_bf16 v[70:73], v[150:153], v[212:215], v[70:73]
	v_mfma_f32_16x16x32_bf16 v[66:69], v[158:161], v[212:215], v[66:69]
	s_setprio 0
	s_barrier
	s_add_i32 s54, s45, s31
	v_lshl_add_u64 v[216:217], s[26:27], 0, v[186:187]
	s_mov_b32 m0, s54
	ds_read_b128 v[162:165], v202 offset:16384
	ds_read_b128 v[166:169], v202 offset:17408
	ds_read_b128 v[170:173], v202 offset:18432
	ds_read_b128 v[174:177], v202 offset:19456
	ds_read_b128 v[178:181], v202 offset:20480
	ds_read_b128 v[204:207], v202 offset:21504
	ds_read_b128 v[208:211], v202 offset:22528
	ds_read_b128 v[212:215], v202 offset:23552
	global_load_lds_dwordx4 v[216:217], off
	s_add_i32 m0, s54, 0x2000
	s_add_u32 s54, s26, 0x80000
	v_lshl_add_u64 v[218:219], s[26:27], 0, v[182:183]
	s_addc_u32 s55, s27, 0
	s_add_i32 s56, s46, s31
	global_load_lds_dwordx4 v[218:219], off
	v_lshl_add_u64 v[220:221], s[54:55], 0, v[186:187]
	s_mov_b32 m0, s56
	v_lshl_add_u64 v[222:223], s[28:29], 0, v[184:185]
	global_load_lds_dwordx4 v[220:221], off
	v_lshl_add_u64 v[220:221], s[54:55], 0, v[182:183]
	s_add_i32 m0, s56, 0x2000
	s_nop 0
	global_load_lds_dwordx4 v[220:221], off
	v_lshl_add_u64 v[220:221], s[28:29], 0, v[188:189]
	s_mov_b32 m0, s35
	s_nop 0
	global_load_lds_dwordx4 v[220:221], off
	s_mov_b32 m0, s36
	s_nop 0
	global_load_lds_dwordx4 v[222:223], off
	s_cmp_lg_u32 s32, 0
	s_cbranch_scc1 .Lkw_P6_2
	s_waitcnt vmcnt(8)
.Lkw_P6_2:
	s_mov_b32 s32, 0
	s_waitcnt lgkmcnt(0)
	s_barrier
	s_setprio 1
	s_waitcnt lgkmcnt(0)
	v_mfma_f32_16x16x32_bf16 v[62:65], v[130:133], v[162:165], v[62:65]
	v_mfma_f32_16x16x32_bf16 v[58:61], v[138:141], v[162:165], v[58:61]
	v_mfma_f32_16x16x32_bf16 v[54:57], v[130:133], v[170:173], v[54:57]
	v_mfma_f32_16x16x32_bf16 v[46:49], v[138:141], v[170:173], v[46:49]
	v_mfma_f32_16x16x32_bf16 v[38:41], v[130:133], v[178:181], v[38:41]
	v_mfma_f32_16x16x32_bf16 v[30:33], v[138:141], v[178:181], v[30:33]
	v_mfma_f32_16x16x32_bf16 v[22:25], v[130:133], v[208:211], v[22:25]
	v_mfma_f32_16x16x32_bf16 v[14:17], v[138:141], v[208:211], v[14:17]
	v_mfma_f32_16x16x32_bf16 v[62:65], v[134:137], v[166:169], v[62:65]
	v_mfma_f32_16x16x32_bf16 v[58:61], v[142:145], v[166:169], v[58:61]
	v_mfma_f32_16x16x32_bf16 v[54:57], v[134:137], v[174:177], v[54:57]
	v_mfma_f32_16x16x32_bf16 v[46:49], v[142:145], v[174:177], v[46:49]
	v_mfma_f32_16x16x32_bf16 v[38:41], v[134:137], v[204:207], v[38:41]
	v_mfma_f32_16x16x32_bf16 v[30:33], v[142:145], v[204:207], v[30:33]
	v_mfma_f32_16x16x32_bf16 v[22:25], v[134:137], v[212:215], v[22:25]
	v_mfma_f32_16x16x32_bf16 v[14:17], v[142:145], v[212:215], v[14:17]
	s_setprio 0
	s_setprio 1
	v_mfma_f32_16x16x32_bf16 v[50:53], v[146:149], v[162:165], v[50:53]
	v_mfma_f32_16x16x32_bf16 v[42:45], v[154:157], v[162:165], v[42:45]
	v_mfma_f32_16x16x32_bf16 v[34:37], v[146:149], v[170:173], v[34:37]
	v_mfma_f32_16x16x32_bf16 v[26:29], v[154:157], v[170:173], v[26:29]
	v_mfma_f32_16x16x32_bf16 v[18:21], v[146:149], v[178:181], v[18:21]
	v_mfma_f32_16x16x32_bf16 v[10:13], v[154:157], v[178:181], v[10:13]
	v_mfma_f32_16x16x32_bf16 v[6:9], v[146:149], v[208:211], v[6:9]
	v_mfma_f32_16x16x32_bf16 v[2:5], v[154:157], v[208:211], v[2:5]
	v_mfma_f32_16x16x32_bf16 v[50:53], v[150:153], v[166:169], v[50:53]
	v_mfma_f32_16x16x32_bf16 v[42:45], v[158:161], v[166:169], v[42:45]
	v_mfma_f32_16x16x32_bf16 v[34:37], v[150:153], v[174:177], v[34:37]
	v_mfma_f32_16x16x32_bf16 v[26:29], v[158:161], v[174:177], v[26:29]
	v_mfma_f32_16x16x32_bf16 v[18:21], v[150:153], v[204:207], v[18:21]
	v_mfma_f32_16x16x32_bf16 v[10:13], v[158:161], v[204:207], v[10:13]
	v_mfma_f32_16x16x32_bf16 v[6:9], v[150:153], v[212:215], v[6:9]
	v_mfma_f32_16x16x32_bf16 v[2:5], v[158:161], v[212:215], v[2:5]
	s_setprio 0
	s_barrier
	s_add_i32 s54, 0, 0x18000
	s_add_i32 s55, 0, 0x1c000
	v_add_u32_e32 v142, s54, v199
	v_add_u32_e32 v158, s55, v199
	ds_read_b128 v[130:133], v142
	ds_read_b128 v[134:137], v142 offset:1024
	ds_read_b128 v[138:141], v142 offset:2048
	ds_read_b128 v[142:145], v142 offset:3072
	ds_read_b128 v[146:149], v158
	ds_read_b128 v[150:153], v158 offset:1024
	ds_read_b128 v[154:157], v158 offset:2048
	ds_read_b128 v[158:161], v158 offset:3072
	s_add_u32 s28, s28, 0x80000
	s_addc_u32 s29, s29, 0
	s_mov_b32 m0, s37
	v_lshl_add_u64 v[224:225], s[28:29], 0, v[188:189]
	ds_read_b128 v[162:165], v202 offset:32768
	ds_read_b128 v[166:169], v202 offset:33792
	ds_read_b128 v[170:173], v202 offset:34816
	ds_read_b128 v[174:177], v202 offset:35840
	ds_read_b128 v[178:181], v202 offset:36864
	ds_read_b128 v[204:207], v202 offset:37888
	ds_read_b128 v[208:211], v202 offset:38912
	ds_read_b128 v[212:215], v202 offset:39936
	global_load_lds_dwordx4 v[224:225], off
	v_lshl_add_u64 v[224:225], s[28:29], 0, v[184:185]
	s_mov_b32 m0, s38
	s_nop 0
	global_load_lds_dwordx4 v[224:225], off
	s_waitcnt vmcnt(8)
	s_waitcnt lgkmcnt(0)
	s_barrier
	s_setprio 1
	s_waitcnt lgkmcnt(0)
	v_mfma_f32_16x16x32_bf16 v[126:129], v[130:133], v[162:165], v[126:129]
	v_mfma_f32_16x16x32_bf16 v[122:125], v[138:141], v[162:165], v[122:125]
	v_mfma_f32_16x16x32_bf16 v[118:121], v[130:133], v[170:173], v[118:121]
	v_mfma_f32_16x16x32_bf16 v[110:113], v[138:141], v[170:173], v[110:113]
	v_mfma_f32_16x16x32_bf16 v[102:105], v[130:133], v[178:181], v[102:105]
	v_mfma_f32_16x16x32_bf16 v[94:97], v[138:141], v[178:181], v[94:97]
	v_mfma_f32_16x16x32_bf16 v[86:89], v[130:133], v[208:211], v[86:89]
	v_mfma_f32_16x16x32_bf16 v[78:81], v[138:141], v[208:211], v[78:81]
	v_mfma_f32_16x16x32_bf16 v[126:129], v[134:137], v[166:169], v[126:129]
	v_mfma_f32_16x16x32_bf16 v[122:125], v[142:145], v[166:169], v[122:125]
	v_mfma_f32_16x16x32_bf16 v[118:121], v[134:137], v[174:177], v[118:121]
	v_mfma_f32_16x16x32_bf16 v[110:113], v[142:145], v[174:177], v[110:113]
	v_mfma_f32_16x16x32_bf16 v[102:105], v[134:137], v[204:207], v[102:105]
	v_mfma_f32_16x16x32_bf16 v[94:97], v[142:145], v[204:207], v[94:97]
	v_mfma_f32_16x16x32_bf16 v[86:89], v[134:137], v[212:215], v[86:89]
	v_mfma_f32_16x16x32_bf16 v[78:81], v[142:145], v[212:215], v[78:81]
	s_setprio 0
	s_setprio 1
	v_mfma_f32_16x16x32_bf16 v[114:117], v[146:149], v[162:165], v[114:117]
	v_mfma_f32_16x16x32_bf16 v[106:109], v[154:157], v[162:165], v[106:109]
	v_mfma_f32_16x16x32_bf16 v[98:101], v[146:149], v[170:173], v[98:101]
	v_mfma_f32_16x16x32_bf16 v[90:93], v[154:157], v[170:173], v[90:93]
	v_mfma_f32_16x16x32_bf16 v[82:85], v[146:149], v[178:181], v[82:85]
	v_mfma_f32_16x16x32_bf16 v[74:77], v[154:157], v[178:181], v[74:77]
	v_mfma_f32_16x16x32_bf16 v[70:73], v[146:149], v[208:211], v[70:73]
	v_mfma_f32_16x16x32_bf16 v[66:69], v[154:157], v[208:211], v[66:69]
	v_mfma_f32_16x16x32_bf16 v[114:117], v[150:153], v[166:169], v[114:117]
	v_mfma_f32_16x16x32_bf16 v[106:109], v[158:161], v[166:169], v[106:109]
	v_mfma_f32_16x16x32_bf16 v[98:101], v[150:153], v[174:177], v[98:101]
	v_mfma_f32_16x16x32_bf16 v[90:93], v[158:161], v[174:177], v[90:93]
	v_mfma_f32_16x16x32_bf16 v[82:85], v[150:153], v[204:207], v[82:85]
	v_mfma_f32_16x16x32_bf16 v[74:77], v[158:161], v[204:207], v[74:77]
	v_mfma_f32_16x16x32_bf16 v[70:73], v[150:153], v[212:215], v[70:73]
	v_mfma_f32_16x16x32_bf16 v[66:69], v[158:161], v[212:215], v[66:69]
	s_setprio 0
	s_barrier
	s_add_i32 s28, s54, s31
	v_lshl_add_u64 v[216:217], v[216:217], 0, s[12:13]
	s_mov_b32 m0, s28
	ds_read_b128 v[162:165], v202 offset:49152
	ds_read_b128 v[166:169], v202 offset:50176
	ds_read_b128 v[170:173], v202 offset:51200
	ds_read_b128 v[174:177], v202 offset:52224
	ds_read_b128 v[178:181], v202 offset:53248
	ds_read_b128 v[204:207], v202 offset:54272
	ds_read_b128 v[208:211], v202 offset:55296
	ds_read_b128 v[212:215], v202 offset:56320
	global_load_lds_dwordx4 v[216:217], off
	s_add_i32 m0, s28, 0x2000
	s_add_u32 s26, s26, 0x80080
	v_lshl_add_u64 v[216:217], v[218:219], 0, s[12:13]
	s_addc_u32 s27, s27, 0
	s_add_i32 s28, s55, s31
	global_load_lds_dwordx4 v[216:217], off
	v_lshl_add_u64 v[216:217], s[26:27], 0, v[186:187]
	s_mov_b32 m0, s28
	s_nop 0
	global_load_lds_dwordx4 v[216:217], off
	v_lshl_add_u64 v[216:217], s[26:27], 0, v[182:183]
	s_add_i32 m0, s28, 0x2000
	s_nop 0
	global_load_lds_dwordx4 v[216:217], off
	v_lshl_add_u64 v[216:217], v[220:221], 0, s[12:13]
	s_mov_b32 m0, s42
	s_nop 0
	global_load_lds_dwordx4 v[216:217], off
	v_lshl_add_u64 v[216:217], v[222:223], 0, s[12:13]
	s_mov_b32 m0, s43
	s_nop 0
	global_load_lds_dwordx4 v[216:217], off
	s_waitcnt vmcnt(8)
	s_waitcnt lgkmcnt(0)
	s_barrier
	s_setprio 1
	s_waitcnt lgkmcnt(0)
	v_mfma_f32_16x16x32_bf16 v[62:65], v[130:133], v[162:165], v[62:65]
	v_mfma_f32_16x16x32_bf16 v[58:61], v[138:141], v[162:165], v[58:61]
	v_mfma_f32_16x16x32_bf16 v[54:57], v[130:133], v[170:173], v[54:57]
	v_mfma_f32_16x16x32_bf16 v[46:49], v[138:141], v[170:173], v[46:49]
	v_mfma_f32_16x16x32_bf16 v[38:41], v[130:133], v[178:181], v[38:41]
	v_mfma_f32_16x16x32_bf16 v[30:33], v[138:141], v[178:181], v[30:33]
	v_mfma_f32_16x16x32_bf16 v[22:25], v[130:133], v[208:211], v[22:25]
	v_mfma_f32_16x16x32_bf16 v[14:17], v[138:141], v[208:211], v[14:17]
	v_mfma_f32_16x16x32_bf16 v[62:65], v[134:137], v[166:169], v[62:65]
	v_mfma_f32_16x16x32_bf16 v[58:61], v[142:145], v[166:169], v[58:61]
	v_mfma_f32_16x16x32_bf16 v[54:57], v[134:137], v[174:177], v[54:57]
	v_mfma_f32_16x16x32_bf16 v[46:49], v[142:145], v[174:177], v[46:49]
	v_mfma_f32_16x16x32_bf16 v[38:41], v[134:137], v[204:207], v[38:41]
	v_mfma_f32_16x16x32_bf16 v[30:33], v[142:145], v[204:207], v[30:33]
	v_mfma_f32_16x16x32_bf16 v[22:25], v[134:137], v[212:215], v[22:25]
	v_mfma_f32_16x16x32_bf16 v[14:17], v[142:145], v[212:215], v[14:17]
	s_setprio 0
	s_setprio 1
	v_mfma_f32_16x16x32_bf16 v[50:53], v[146:149], v[162:165], v[50:53]
	v_mfma_f32_16x16x32_bf16 v[42:45], v[154:157], v[162:165], v[42:45]
	v_mfma_f32_16x16x32_bf16 v[34:37], v[146:149], v[170:173], v[34:37]
	v_mfma_f32_16x16x32_bf16 v[26:29], v[154:157], v[170:173], v[26:29]
	v_mfma_f32_16x16x32_bf16 v[18:21], v[146:149], v[178:181], v[18:21]
	v_mfma_f32_16x16x32_bf16 v[10:13], v[154:157], v[178:181], v[10:13]
	v_mfma_f32_16x16x32_bf16 v[6:9], v[146:149], v[208:211], v[6:9]
	v_mfma_f32_16x16x32_bf16 v[2:5], v[154:157], v[208:211], v[2:5]
	v_mfma_f32_16x16x32_bf16 v[50:53], v[150:153], v[166:169], v[50:53]
	v_mfma_f32_16x16x32_bf16 v[42:45], v[158:161], v[166:169], v[42:45]
	v_mfma_f32_16x16x32_bf16 v[34:37], v[150:153], v[174:177], v[34:37]
	v_mfma_f32_16x16x32_bf16 v[26:29], v[158:161], v[174:177], v[26:29]
	v_mfma_f32_16x16x32_bf16 v[18:21], v[150:153], v[204:207], v[18:21]
	v_mfma_f32_16x16x32_bf16 v[10:13], v[158:161], v[204:207], v[10:13]
	v_mfma_f32_16x16x32_bf16 v[6:9], v[150:153], v[212:215], v[6:9]
	v_mfma_f32_16x16x32_bf16 v[2:5], v[158:161], v[212:215], v[2:5]
	s_setprio 0
	s_barrier
	s_add_i32 s53, s53, 2
	s_add_u32 s8, s8, 0x100
	s_addc_u32 s9, s9, 0
	s_add_u32 s51, s51, 0x100
	s_addc_u32 s52, s52, 0
	s_cmp_gt_u32 s53, 29
	s_cbranch_scc0 .LBB0_1942
	s_mov_b32 s32, 1
	s_and_b64 vcc, exec, s[14:15]
	s_cbranch_vccz .LBB0_1945
	s_barrier

.LBB0_2094:
	v_readlane_b32 s2, v254, 5
	v_readlane_b32 s3, v254, 6
	s_cmp_lt_i32 s2, 9
	s_cselect_b64 s[2:3], -1, 0
	s_and_b64 s[2:3], s[2:3], s[0:1]
	s_andn2_b64 vcc, exec, s[2:3]
	s_cbranch_vccnz .LBB0_2141
	s_mov_b32 s32, 0
	s_waitcnt vmcnt(5)
	v_mov_b32_e32 v10, v0
	s_cmpk_lt_i32 s86, 0x200
	s_cselect_b64 s[0:1], -1, 0
	s_cmpk_gt_i32 s86, 0x1ff
	v_readfirstlane_b32 s6, v10
	s_cbranch_scc1 .LBB0_2101
	s_ashr_i32 s4, s86, 31
	s_lshr_b32 s4, s4, 29
	s_add_i32 s7, s86, s4
	s_and_b32 s4, s7, -8
	s_sub_i32 s8, s86, s4
	s_cmp_gt_i32 s8, -1
	s_cbranch_scc0 .LBB0_2098
	s_lshl_b32 s9, s8, 6
	s_cbranch_execz .LBB0_2099
	s_branch .LBB0_2100

.LBB0_2118:
	ds_read_b128 v[142:145], v148
	ds_read_b128 v[152:155], v148 offset:1024
	ds_read_b128 v[156:159], v148 offset:2048
	ds_read_b128 v[160:163], v148 offset:3072
	ds_read_b128 v[164:167], v149
	ds_read_b128 v[168:171], v149 offset:1024
	ds_read_b128 v[172:175], v149 offset:2048
	ds_read_b128 v[176:179], v149 offset:3072
	s_add_u32 s20, s18, 0x100
	s_addc_u32 s21, s19, 0
	s_cmpk_eq_i32 s49, 0x54
	s_cselect_b32 s25, s7, s21
	s_cselect_b32 s24, s6, s20
	s_cselect_b32 s23, s17, s48
	s_cselect_b32 s22, s16, s47
	v_lshl_add_u64 v[212:213], s[18:19], 0, v[134:135]
	s_add_i32 m0, s30, 0xc000
	ds_read_b128 v[180:183], v150
	ds_read_b128 v[184:187], v150 offset:1024
	ds_read_b128 v[188:191], v150 offset:2048
	ds_read_b128 v[192:195], v150 offset:3072
	ds_read_b128 v[196:199], v150 offset:4096
	ds_read_b128 v[200:203], v150 offset:5120
	ds_read_b128 v[204:207], v150 offset:6144
	ds_read_b128 v[208:211], v150 offset:7168
	global_load_lds_dwordx4 v[212:213], off
	v_lshl_add_u64 v[212:213], s[18:19], 0, v[136:137]
	s_add_i32 m0, s30, 0xe000
	s_nop 0
	global_load_lds_dwordx4 v[212:213], off
	s_cmp_lg_u32 s32, 0
	s_cbranch_scc1 .Lkw_P8_1
	s_waitcnt vmcnt(8)
.Lkw_P8_1:
	s_waitcnt lgkmcnt(0)
	s_barrier
	s_setprio 1
	s_waitcnt lgkmcnt(0)
	v_mfma_f32_16x16x32_bf16 v[126:129], v[142:145], v[180:183], v[126:129]
	v_mfma_f32_16x16x32_bf16 v[122:125], v[156:159], v[180:183], v[122:125]
	v_mfma_f32_16x16x32_bf16 v[110:113], v[142:145], v[188:191], v[110:113]
	v_mfma_f32_16x16x32_bf16 v[106:109], v[156:159], v[188:191], v[106:109]
	v_mfma_f32_16x16x32_bf16 v[94:97], v[142:145], v[196:199], v[94:97]
	v_mfma_f32_16x16x32_bf16 v[90:93], v[156:159], v[196:199], v[90:93]
	v_mfma_f32_16x16x32_bf16 v[78:81], v[142:145], v[204:207], v[78:81]
	v_mfma_f32_16x16x32_bf16 v[74:77], v[156:159], v[204:207], v[74:77]
	v_mfma_f32_16x16x32_bf16 v[126:129], v[152:155], v[184:187], v[126:129]
	v_mfma_f32_16x16x32_bf16 v[122:125], v[160:163], v[184:187], v[122:125]
	v_mfma_f32_16x16x32_bf16 v[110:113], v[152:155], v[192:195], v[110:113]
	v_mfma_f32_16x16x32_bf16 v[106:109], v[160:163], v[192:195], v[106:109]
	v_mfma_f32_16x16x32_bf16 v[94:97], v[152:155], v[200:203], v[94:97]
	v_mfma_f32_16x16x32_bf16 v[90:93], v[160:163], v[200:203], v[90:93]
	v_mfma_f32_16x16x32_bf16 v[78:81], v[152:155], v[208:211], v[78:81]
	v_mfma_f32_16x16x32_bf16 v[74:77], v[160:163], v[208:211], v[74:77]
	s_setprio 0
	s_setprio 1
	v_mfma_f32_16x16x32_bf16 v[118:121], v[164:167], v[180:183], v[118:121]
	v_mfma_f32_16x16x32_bf16 v[114:117], v[172:175], v[180:183], v[114:117]
	v_mfma_f32_16x16x32_bf16 v[102:105], v[164:167], v[188:191], v[102:105]
	v_mfma_f32_16x16x32_bf16 v[98:101], v[172:175], v[188:191], v[98:101]
	v_mfma_f32_16x16x32_bf16 v[86:89], v[164:167], v[196:199], v[86:89]
	v_mfma_f32_16x16x32_bf16 v[82:85], v[172:175], v[196:199], v[82:85]
	v_mfma_f32_16x16x32_bf16 v[70:73], v[164:167], v[204:207], v[70:73]
	v_mfma_f32_16x16x32_bf16 v[66:69], v[172:175], v[204:207], v[66:69]
	v_mfma_f32_16x16x32_bf16 v[118:121], v[168:171], v[184:187], v[118:121]
	v_mfma_f32_16x16x32_bf16 v[114:117], v[176:179], v[184:187], v[114:117]
	v_mfma_f32_16x16x32_bf16 v[102:105], v[168:171], v[192:195], v[102:105]
	v_mfma_f32_16x16x32_bf16 v[98:101], v[176:179], v[192:195], v[98:101]
	v_mfma_f32_16x16x32_bf16 v[86:89], v[168:171], v[200:203], v[86:89]
	v_mfma_f32_16x16x32_bf16 v[82:85], v[176:179], v[200:203], v[82:85]
	v_mfma_f32_16x16x32_bf16 v[70:73], v[168:171], v[208:211], v[70:73]
	v_mfma_f32_16x16x32_bf16 v[66:69], v[176:179], v[208:211], v[66:69]
	s_setprio 0
	s_barrier
	s_add_i32 s18, s42, s29
	v_lshl_add_u64 v[212:213], s[22:23], 0, v[130:131]
	s_mov_b32 m0, s18
	ds_read_b128 v[180:183], v150 offset:16384
	ds_read_b128 v[184:187], v150 offset:17408
	ds_read_b128 v[188:191], v150 offset:18432
	ds_read_b128 v[192:195], v150 offset:19456
	ds_read_b128 v[196:199], v150 offset:20480
	ds_read_b128 v[200:203], v150 offset:21504
	ds_read_b128 v[204:207], v150 offset:22528
	ds_read_b128 v[208:211], v150 offset:23552
	global_load_lds_dwordx4 v[212:213], off
	s_add_i32 m0, s18, 0x2000
	s_add_u32 s18, s22, 0x160000
	v_lshl_add_u64 v[214:215], s[22:23], 0, v[132:133]
	s_addc_u32 s19, s23, 0
	s_add_i32 s50, s43, s29
	global_load_lds_dwordx4 v[214:215], off
	v_lshl_add_u64 v[216:217], s[18:19], 0, v[130:131]
	s_mov_b32 m0, s50
	v_lshl_add_u64 v[218:219], s[24:25], 0, v[132:133]
	global_load_lds_dwordx4 v[216:217], off
	v_lshl_add_u64 v[216:217], s[18:19], 0, v[132:133]
	s_add_i32 m0, s50, 0x2000
	s_nop 0
	global_load_lds_dwordx4 v[216:217], off
	v_lshl_add_u64 v[216:217], s[24:25], 0, v[130:131]
	s_mov_b32 m0, s30
	s_nop 0
	global_load_lds_dwordx4 v[216:217], off
	s_mov_b32 m0, s31
	s_nop 0
	global_load_lds_dwordx4 v[218:219], off
	s_cmp_lg_u32 s32, 0
	s_cbranch_scc1 .Lkw_P8_2
	s_waitcnt vmcnt(8)
.Lkw_P8_2:
	s_mov_b32 s32, 0
	s_waitcnt lgkmcnt(0)
	s_barrier
	s_setprio 1
	s_waitcnt lgkmcnt(0)
	v_mfma_f32_16x16x32_bf16 v[62:65], v[142:145], v[180:183], v[62:65]
	v_mfma_f32_16x16x32_bf16 v[58:61], v[156:159], v[180:183], v[58:61]
	v_mfma_f32_16x16x32_bf16 v[46:49], v[142:145], v[188:191], v[46:49]
	v_mfma_f32_16x16x32_bf16 v[42:45], v[156:159], v[188:191], v[42:45]
	v_mfma_f32_16x16x32_bf16 v[30:33], v[142:145], v[196:199], v[30:33]
	v_mfma_f32_16x16x32_bf16 v[26:29], v[156:159], v[196:199], v[26:29]
	v_mfma_f32_16x16x32_bf16 v[14:17], v[142:145], v[204:207], v[14:17]
	v_mfma_f32_16x16x32_bf16 v[10:13], v[156:159], v[204:207], v[10:13]
	v_mfma_f32_16x16x32_bf16 v[62:65], v[152:155], v[184:187], v[62:65]
	v_mfma_f32_16x16x32_bf16 v[58:61], v[160:163], v[184:187], v[58:61]
	v_mfma_f32_16x16x32_bf16 v[46:49], v[152:155], v[192:195], v[46:49]
	v_mfma_f32_16x16x32_bf16 v[42:45], v[160:163], v[192:195], v[42:45]
	v_mfma_f32_16x16x32_bf16 v[30:33], v[152:155], v[200:203], v[30:33]
	v_mfma_f32_16x16x32_bf16 v[26:29], v[160:163], v[200:203], v[26:29]
	v_mfma_f32_16x16x32_bf16 v[14:17], v[152:155], v[208:211], v[14:17]
	v_mfma_f32_16x16x32_bf16 v[10:13], v[160:163], v[208:211], v[10:13]
	s_setprio 0
	s_setprio 1
	v_mfma_f32_16x16x32_bf16 v[54:57], v[164:167], v[180:183], v[54:57]
	v_mfma_f32_16x16x32_bf16 v[50:53], v[172:175], v[180:183], v[50:53]
	v_mfma_f32_16x16x32_bf16 v[38:41], v[164:167], v[188:191], v[38:41]
	v_mfma_f32_16x16x32_bf16 v[34:37], v[172:175], v[188:191], v[34:37]
	v_mfma_f32_16x16x32_bf16 v[22:25], v[164:167], v[196:199], v[22:25]
	v_mfma_f32_16x16x32_bf16 v[18:21], v[172:175], v[196:199], v[18:21]
	v_mfma_f32_16x16x32_bf16 v[6:9], v[164:167], v[204:207], v[6:9]
	v_mfma_f32_16x16x32_bf16 v[2:5], v[172:175], v[204:207], v[2:5]
	v_mfma_f32_16x16x32_bf16 v[54:57], v[168:171], v[184:187], v[54:57]
	v_mfma_f32_16x16x32_bf16 v[50:53], v[176:179], v[184:187], v[50:53]
	v_mfma_f32_16x16x32_bf16 v[38:41], v[168:171], v[192:195], v[38:41]
	v_mfma_f32_16x16x32_bf16 v[34:37], v[176:179], v[192:195], v[34:37]
	v_mfma_f32_16x16x32_bf16 v[22:25], v[168:171], v[200:203], v[22:25]
	v_mfma_f32_16x16x32_bf16 v[18:21], v[176:179], v[200:203], v[18:21]
	v_mfma_f32_16x16x32_bf16 v[6:9], v[168:171], v[208:211], v[6:9]
	v_mfma_f32_16x16x32_bf16 v[2:5], v[176:179], v[208:211], v[2:5]
	s_setprio 0
	s_barrier
	s_add_i32 s50, 0, 0x18000
	s_add_i32 s51, 0, 0x1c000
	v_add_u32_e32 v160, s50, v147
	v_add_u32_e32 v176, s51, v147
	ds_read_b128 v[142:145], v160
	ds_read_b128 v[152:155], v160 offset:1024
	ds_read_b128 v[156:159], v160 offset:2048
	ds_read_b128 v[160:163], v160 offset:3072
	ds_read_b128 v[164:167], v176
	ds_read_b128 v[168:171], v176 offset:1024
	ds_read_b128 v[172:175], v176 offset:2048
	ds_read_b128 v[176:179], v176 offset:3072
	s_add_u32 s18, s24, 0x160000
	s_addc_u32 s19, s25, 0
	s_mov_b32 m0, s33
	v_lshl_add_u64 v[220:221], s[18:19], 0, v[130:131]
	ds_read_b128 v[180:183], v150 offset:32768
	ds_read_b128 v[184:187], v150 offset:33792
	ds_read_b128 v[188:191], v150 offset:34816
	ds_read_b128 v[192:195], v150 offset:35840
	ds_read_b128 v[196:199], v150 offset:36864
	ds_read_b128 v[200:203], v150 offset:37888
	ds_read_b128 v[204:207], v150 offset:38912
	ds_read_b128 v[208:211], v150 offset:39936
	global_load_lds_dwordx4 v[220:221], off
	v_lshl_add_u64 v[220:221], s[18:19], 0, v[132:133]
	s_mov_b32 m0, s34
	s_nop 0
	global_load_lds_dwordx4 v[220:221], off
	s_waitcnt vmcnt(8)
	s_waitcnt lgkmcnt(0)
	s_barrier
	s_setprio 1
	s_waitcnt lgkmcnt(0)
	v_mfma_f32_16x16x32_bf16 v[126:129], v[142:145], v[180:183], v[126:129]
	v_mfma_f32_16x16x32_bf16 v[122:125], v[156:159], v[180:183], v[122:125]
	v_mfma_f32_16x16x32_bf16 v[110:113], v[142:145], v[188:191], v[110:113]
	v_mfma_f32_16x16x32_bf16 v[106:109], v[156:159], v[188:191], v[106:109]
	v_mfma_f32_16x16x32_bf16 v[94:97], v[142:145], v[196:199], v[94:97]
	v_mfma_f32_16x16x32_bf16 v[90:93], v[156:159], v[196:199], v[90:93]
	v_mfma_f32_16x16x32_bf16 v[78:81], v[142:145], v[204:207], v[78:81]
	v_mfma_f32_16x16x32_bf16 v[74:77], v[156:159], v[204:207], v[74:77]
	v_mfma_f32_16x16x32_bf16 v[126:129], v[152:155], v[184:187], v[126:129]
	v_mfma_f32_16x16x32_bf16 v[122:125], v[160:163], v[184:187], v[122:125]
	v_mfma_f32_16x16x32_bf16 v[110:113], v[152:155], v[192:195], v[110:113]
	v_mfma_f32_16x16x32_bf16 v[106:109], v[160:163], v[192:195], v[106:109]
	v_mfma_f32_16x16x32_bf16 v[94:97], v[152:155], v[200:203], v[94:97]
	v_mfma_f32_16x16x32_bf16 v[90:93], v[160:163], v[200:203], v[90:93]
	v_mfma_f32_16x16x32_bf16 v[78:81], v[152:155], v[208:211], v[78:81]
	v_mfma_f32_16x16x32_bf16 v[74:77], v[160:163], v[208:211], v[74:77]
	s_setprio 0
	s_setprio 1
	v_mfma_f32_16x16x32_bf16 v[118:121], v[164:167], v[180:183], v[118:121]
	v_mfma_f32_16x16x32_bf16 v[114:117], v[172:175], v[180:183], v[114:117]
	v_mfma_f32_16x16x32_bf16 v[102:105], v[164:167], v[188:191], v[102:105]
	v_mfma_f32_16x16x32_bf16 v[98:101], v[172:175], v[188:191], v[98:101]
	v_mfma_f32_16x16x32_bf16 v[86:89], v[164:167], v[196:199], v[86:89]
	v_mfma_f32_16x16x32_bf16 v[82:85], v[172:175], v[196:199], v[82:85]
	v_mfma_f32_16x16x32_bf16 v[70:73], v[164:167], v[204:207], v[70:73]
	v_mfma_f32_16x16x32_bf16 v[66:69], v[172:175], v[204:207], v[66:69]
	v_mfma_f32_16x16x32_bf16 v[118:121], v[168:171], v[184:187], v[118:121]
	v_mfma_f32_16x16x32_bf16 v[114:117], v[176:179], v[184:187], v[114:117]
	v_mfma_f32_16x16x32_bf16 v[102:105], v[168:171], v[192:195], v[102:105]
	v_mfma_f32_16x16x32_bf16 v[98:101], v[176:179], v[192:195], v[98:101]
	v_mfma_f32_16x16x32_bf16 v[86:89], v[168:171], v[200:203], v[86:89]
	v_mfma_f32_16x16x32_bf16 v[82:85], v[176:179], v[200:203], v[82:85]
	v_mfma_f32_16x16x32_bf16 v[70:73], v[168:171], v[208:211], v[70:73]
	v_mfma_f32_16x16x32_bf16 v[66:69], v[176:179], v[208:211], v[66:69]
	s_setprio 0
	s_barrier
	s_add_i32 s18, s50, s29
	v_lshl_add_u64 v[212:213], v[212:213], 0, s[12:13]
	s_mov_b32 m0, s18
	ds_read_b128 v[180:183], v150 offset:49152
	ds_read_b128 v[184:187], v150 offset:50176
	ds_read_b128 v[188:191], v150 offset:51200
	ds_read_b128 v[192:195], v150 offset:52224
	ds_read_b128 v[196:199], v150 offset:53248
	ds_read_b128 v[200:203], v150 offset:54272
	ds_read_b128 v[204:207], v150 offset:55296
	ds_read_b128 v[208:211], v150 offset:56320
	global_load_lds_dwordx4 v[212:213], off
	s_add_i32 m0, s18, 0x2000
	s_add_u32 s18, s22, 0x160080
	v_lshl_add_u64 v[212:213], v[214:215], 0, s[12:13]
	s_addc_u32 s19, s23, 0
	s_add_i32 s22, s51, s29
	global_load_lds_dwordx4 v[212:213], off
	v_lshl_add_u64 v[212:213], s[18:19], 0, v[130:131]
	s_mov_b32 m0, s22
	s_nop 0
	global_load_lds_dwordx4 v[212:213], off
	v_lshl_add_u64 v[212:213], s[18:19], 0, v[132:133]
	s_add_i32 m0, s22, 0x2000
	s_nop 0
	global_load_lds_dwordx4 v[212:213], off
	v_lshl_add_u64 v[212:213], v[216:217], 0, s[12:13]
	s_mov_b32 m0, s38
	s_nop 0
	global_load_lds_dwordx4 v[212:213], off
	v_lshl_add_u64 v[212:213], v[218:219], 0, s[12:13]
	s_mov_b32 m0, s39
	s_nop 0
	global_load_lds_dwordx4 v[212:213], off
	s_waitcnt vmcnt(8)
	s_waitcnt lgkmcnt(0)
	s_barrier
	s_setprio 1
	s_waitcnt lgkmcnt(0)
	v_mfma_f32_16x16x32_bf16 v[62:65], v[142:145], v[180:183], v[62:65]
	v_mfma_f32_16x16x32_bf16 v[58:61], v[156:159], v[180:183], v[58:61]
	v_mfma_f32_16x16x32_bf16 v[46:49], v[142:145], v[188:191], v[46:49]
	v_mfma_f32_16x16x32_bf16 v[42:45], v[156:159], v[188:191], v[42:45]
	v_mfma_f32_16x16x32_bf16 v[30:33], v[142:145], v[196:199], v[30:33]
	v_mfma_f32_16x16x32_bf16 v[26:29], v[156:159], v[196:199], v[26:29]
	v_mfma_f32_16x16x32_bf16 v[14:17], v[142:145], v[204:207], v[14:17]
	v_mfma_f32_16x16x32_bf16 v[10:13], v[156:159], v[204:207], v[10:13]
	v_mfma_f32_16x16x32_bf16 v[62:65], v[152:155], v[184:187], v[62:65]
	v_mfma_f32_16x16x32_bf16 v[58:61], v[160:163], v[184:187], v[58:61]
	v_mfma_f32_16x16x32_bf16 v[46:49], v[152:155], v[192:195], v[46:49]
	v_mfma_f32_16x16x32_bf16 v[42:45], v[160:163], v[192:195], v[42:45]
	v_mfma_f32_16x16x32_bf16 v[30:33], v[152:155], v[200:203], v[30:33]
	v_mfma_f32_16x16x32_bf16 v[26:29], v[160:163], v[200:203], v[26:29]
	v_mfma_f32_16x16x32_bf16 v[14:17], v[152:155], v[208:211], v[14:17]
	v_mfma_f32_16x16x32_bf16 v[10:13], v[160:163], v[208:211], v[10:13]
	s_setprio 0
	s_setprio 1
	v_mfma_f32_16x16x32_bf16 v[54:57], v[164:167], v[180:183], v[54:57]
	v_mfma_f32_16x16x32_bf16 v[50:53], v[172:175], v[180:183], v[50:53]
	v_mfma_f32_16x16x32_bf16 v[38:41], v[164:167], v[188:191], v[38:41]
	v_mfma_f32_16x16x32_bf16 v[34:37], v[172:175], v[188:191], v[34:37]
	v_mfma_f32_16x16x32_bf16 v[22:25], v[164:167], v[196:199], v[22:25]
	v_mfma_f32_16x16x32_bf16 v[18:21], v[172:175], v[196:199], v[18:21]
	v_mfma_f32_16x16x32_bf16 v[6:9], v[164:167], v[204:207], v[6:9]
	v_mfma_f32_16x16x32_bf16 v[2:5], v[172:175], v[204:207], v[2:5]
	v_mfma_f32_16x16x32_bf16 v[54:57], v[168:171], v[184:187], v[54:57]
	v_mfma_f32_16x16x32_bf16 v[50:53], v[176:179], v[184:187], v[50:53]
	v_mfma_f32_16x16x32_bf16 v[38:41], v[168:171], v[192:195], v[38:41]
	v_mfma_f32_16x16x32_bf16 v[34:37], v[176:179], v[192:195], v[34:37]
	v_mfma_f32_16x16x32_bf16 v[22:25], v[168:171], v[200:203], v[22:25]
	v_mfma_f32_16x16x32_bf16 v[18:21], v[176:179], v[200:203], v[18:21]
	v_mfma_f32_16x16x32_bf16 v[6:9], v[168:171], v[208:211], v[6:9]
	v_mfma_f32_16x16x32_bf16 v[2:5], v[176:179], v[208:211], v[2:5]
	s_setprio 0
	s_barrier
	s_add_i32 s49, s49, 2
	s_add_u32 s47, s47, 0x100
	s_addc_u32 s48, s48, 0
	s_cmpk_gt_u32 s49, 0x55
	s_mov_b64 s[18:19], s[20:21]
	s_cbranch_scc0 .LBB0_2118
	s_mov_b32 s32, 1
	s_and_b64 vcc, exec, s[14:15]
	s_cbranch_vccz .LBB0_2121
	s_barrier

.LBB0_2195:
	v_readlane_b32 s2, v254, 5
	v_readlane_b32 s3, v254, 6
	s_cmp_lt_i32 s2, 10
	s_cselect_b64 s[2:3], -1, 0
	s_and_b64 s[2:3], s[2:3], s[0:1]
	s_andn2_b64 vcc, exec, s[2:3]
	s_cbranch_vccnz .LBB0_2347
	s_mov_b32 s32, 0
	s_waitcnt vmcnt(5)
	v_mov_b32_e32 v11, v0
	s_cmpk_lt_i32 s86, 0x600
	s_cselect_b64 s[0:1], -1, 0
	s_cmpk_gt_i32 s86, 0x5ff
	v_readfirstlane_b32 s16, v11
	s_cbranch_scc1 .LBB0_2198
	s_ashr_i32 s4, s86, 31
	s_lshr_b32 s4, s4, 29
	s_add_i32 s4, s86, s4
	s_ashr_i32 s5, s4, 3
	s_and_b32 s4, s4, -8
	s_sub_i32 s4, s86, s4
	s_cmp_lt_i32 s4, 0
	s_movk_i32 s6, 0xc1
	s_cselect_b32 s6, s6, 0xc0
	s_mul_i32 s4, s4, s6
	s_add_i32 s4, s4, s5
	s_mul_hi_i32 s5, s4, 0x2aaaaaab
	s_lshr_b32 s6, s5, 31
	s_ashr_i32 s5, s5, 4
	s_add_i32 s5, s5, s6
	s_lshl_b32 s6, s5, 2
	s_mulk_i32 s5, 0x60
	s_sub_i32 s4, s4, s5
	s_bfe_i32 s5, s4, 0x80000
	s_bfe_u32 s5, s5, 0x2000d
	s_add_i32 s5, s4, s5
	s_bfe_i32 s7, s5, 0x80000
	s_and_b32 s5, s5, 0xfc
	s_sub_i32 s4, s4, s5
	s_sext_i32_i16 s7, s7
	s_sext_i32_i8 s4, s4
	s_add_i32 s6, s6, s4
	s_ashr_i32 s8, s7, 2

.LBB0_2207:
	ds_read_b128 v[130:133], v197
	ds_read_b128 v[134:137], v197 offset:1024
	ds_read_b128 v[138:141], v197 offset:2048
	ds_read_b128 v[142:145], v197 offset:3072
	ds_read_b128 v[146:149], v198
	ds_read_b128 v[150:153], v198 offset:1024
	ds_read_b128 v[154:157], v198 offset:2048
	ds_read_b128 v[158:161], v198 offset:3072
	s_add_u32 s28, s10, 0xfff80080
	s_addc_u32 s29, s11, -1
	s_cmp_eq_u32 s36, 28
	s_cselect_b32 s31, s7, s29
	s_cselect_b32 s30, s9, s28
	s_cselect_b32 s29, s21, s35
	s_cselect_b32 s28, s23, s34
	v_lshl_add_u64 v[194:195], s[10:11], 0, v[184:185]
	s_add_i32 m0, s39, 0xc000
	ds_read_b128 v[162:165], v199
	ds_read_b128 v[166:169], v199 offset:1024
	ds_read_b128 v[170:173], v199 offset:2048
	ds_read_b128 v[174:177], v199 offset:3072
	ds_read_b128 v[202:205], v199 offset:4096
	ds_read_b128 v[206:209], v199 offset:5120
	ds_read_b128 v[210:213], v199 offset:6144
	ds_read_b128 v[214:217], v199 offset:7168
	global_load_lds_dwordx4 v[194:195], off
	v_lshl_add_u64 v[194:195], s[10:11], 0, v[186:187]
	s_add_i32 m0, s39, 0xe000
	s_nop 0
	global_load_lds_dwordx4 v[194:195], off
	s_cmp_lg_u32 s32, 0
	s_cbranch_scc1 .Lkw_P9_1
	s_waitcnt vmcnt(8)
.Lkw_P9_1:
	s_waitcnt lgkmcnt(0)
	s_barrier
	s_setprio 1
	s_waitcnt lgkmcnt(0)
	v_mfma_f32_16x16x32_bf16 v[126:129], v[130:133], v[162:165], v[126:129]
	v_mfma_f32_16x16x32_bf16 v[122:125], v[138:141], v[162:165], v[122:125]
	v_mfma_f32_16x16x32_bf16 v[110:113], v[130:133], v[170:173], v[110:113]
	v_mfma_f32_16x16x32_bf16 v[106:109], v[138:141], v[170:173], v[106:109]
	v_mfma_f32_16x16x32_bf16 v[94:97], v[130:133], v[202:205], v[94:97]
	v_mfma_f32_16x16x32_bf16 v[90:93], v[138:141], v[202:205], v[90:93]
	v_mfma_f32_16x16x32_bf16 v[78:81], v[130:133], v[210:213], v[78:81]
	v_mfma_f32_16x16x32_bf16 v[74:77], v[138:141], v[210:213], v[74:77]
	v_mfma_f32_16x16x32_bf16 v[126:129], v[134:137], v[166:169], v[126:129]
	v_mfma_f32_16x16x32_bf16 v[122:125], v[142:145], v[166:169], v[122:125]
	v_mfma_f32_16x16x32_bf16 v[110:113], v[134:137], v[174:177], v[110:113]
	v_mfma_f32_16x16x32_bf16 v[106:109], v[142:145], v[174:177], v[106:109]
	v_mfma_f32_16x16x32_bf16 v[94:97], v[134:137], v[206:209], v[94:97]
	v_mfma_f32_16x16x32_bf16 v[90:93], v[142:145], v[206:209], v[90:93]
	v_mfma_f32_16x16x32_bf16 v[78:81], v[134:137], v[214:217], v[78:81]
	v_mfma_f32_16x16x32_bf16 v[74:77], v[142:145], v[214:217], v[74:77]
	s_setprio 0
	s_setprio 1
	v_mfma_f32_16x16x32_bf16 v[118:121], v[146:149], v[162:165], v[118:121]
	v_mfma_f32_16x16x32_bf16 v[114:117], v[154:157], v[162:165], v[114:117]
	v_mfma_f32_16x16x32_bf16 v[102:105], v[146:149], v[170:173], v[102:105]
	v_mfma_f32_16x16x32_bf16 v[98:101], v[154:157], v[170:173], v[98:101]
	v_mfma_f32_16x16x32_bf16 v[86:89], v[146:149], v[202:205], v[86:89]
	v_mfma_f32_16x16x32_bf16 v[82:85], v[154:157], v[202:205], v[82:85]
	v_mfma_f32_16x16x32_bf16 v[70:73], v[146:149], v[210:213], v[70:73]
	v_mfma_f32_16x16x32_bf16 v[66:69], v[154:157], v[210:213], v[66:69]
	v_mfma_f32_16x16x32_bf16 v[118:121], v[150:153], v[166:169], v[118:121]
	v_mfma_f32_16x16x32_bf16 v[114:117], v[158:161], v[166:169], v[114:117]
	v_mfma_f32_16x16x32_bf16 v[102:105], v[150:153], v[174:177], v[102:105]
	v_mfma_f32_16x16x32_bf16 v[98:101], v[158:161], v[174:177], v[98:101]
	v_mfma_f32_16x16x32_bf16 v[86:89], v[150:153], v[206:209], v[86:89]
	v_mfma_f32_16x16x32_bf16 v[82:85], v[158:161], v[206:209], v[82:85]
	v_mfma_f32_16x16x32_bf16 v[70:73], v[150:153], v[214:217], v[70:73]
	v_mfma_f32_16x16x32_bf16 v[66:69], v[158:161], v[214:217], v[66:69]
	s_setprio 0
	s_barrier
	s_add_i32 s37, s52, s38
	v_lshl_add_u64 v[194:195], s[28:29], 0, v[178:179]
	s_mov_b32 m0, s37
	ds_read_b128 v[162:165], v199 offset:16384
	ds_read_b128 v[166:169], v199 offset:17408
	ds_read_b128 v[170:173], v199 offset:18432
	ds_read_b128 v[174:177], v199 offset:19456
	ds_read_b128 v[202:205], v199 offset:20480
	ds_read_b128 v[206:209], v199 offset:21504
	ds_read_b128 v[210:213], v199 offset:22528
	ds_read_b128 v[214:217], v199 offset:23552
	global_load_lds_dwordx4 v[194:195], off
	s_add_i32 m0, s37, 0x2000
	s_add_u32 s56, s28, 0x80000
	v_lshl_add_u64 v[218:219], s[28:29], 0, v[180:181]
	s_addc_u32 s57, s29, 0
	s_add_i32 s37, s53, s38
	global_load_lds_dwordx4 v[218:219], off
	v_lshl_add_u64 v[220:221], s[56:57], 0, v[178:179]
	s_mov_b32 m0, s37
	v_lshl_add_u64 v[222:223], s[30:31], 0, v[180:181]
	global_load_lds_dwordx4 v[220:221], off
	v_lshl_add_u64 v[220:221], s[56:57], 0, v[180:181]
	s_add_i32 m0, s37, 0x2000
	s_nop 0
	global_load_lds_dwordx4 v[220:221], off
	v_lshl_add_u64 v[220:221], s[30:31], 0, v[178:179]
	s_mov_b32 m0, s39
	s_nop 0
	global_load_lds_dwordx4 v[220:221], off
	s_mov_b32 m0, s40
	s_nop 0
	global_load_lds_dwordx4 v[222:223], off
	s_cmp_lg_u32 s32, 0
	s_cbranch_scc1 .Lkw_P9_2
	s_waitcnt vmcnt(8)
.Lkw_P9_2:
	s_mov_b32 s32, 0
	s_waitcnt lgkmcnt(0)
	s_barrier
	s_setprio 1
	s_waitcnt lgkmcnt(0)
	v_mfma_f32_16x16x32_bf16 v[62:65], v[130:133], v[162:165], v[62:65]
	v_mfma_f32_16x16x32_bf16 v[58:61], v[138:141], v[162:165], v[58:61]
	v_mfma_f32_16x16x32_bf16 v[46:49], v[130:133], v[170:173], v[46:49]
	v_mfma_f32_16x16x32_bf16 v[42:45], v[138:141], v[170:173], v[42:45]
	v_mfma_f32_16x16x32_bf16 v[30:33], v[130:133], v[202:205], v[30:33]
	v_mfma_f32_16x16x32_bf16 v[26:29], v[138:141], v[202:205], v[26:29]
	v_mfma_f32_16x16x32_bf16 v[14:17], v[130:133], v[210:213], v[14:17]
	v_mfma_f32_16x16x32_bf16 v[10:13], v[138:141], v[210:213], v[10:13]
	v_mfma_f32_16x16x32_bf16 v[62:65], v[134:137], v[166:169], v[62:65]
	v_mfma_f32_16x16x32_bf16 v[58:61], v[142:145], v[166:169], v[58:61]
	v_mfma_f32_16x16x32_bf16 v[46:49], v[134:137], v[174:177], v[46:49]
	v_mfma_f32_16x16x32_bf16 v[42:45], v[142:145], v[174:177], v[42:45]
	v_mfma_f32_16x16x32_bf16 v[30:33], v[134:137], v[206:209], v[30:33]
	v_mfma_f32_16x16x32_bf16 v[26:29], v[142:145], v[206:209], v[26:29]
	v_mfma_f32_16x16x32_bf16 v[14:17], v[134:137], v[214:217], v[14:17]
	v_mfma_f32_16x16x32_bf16 v[10:13], v[142:145], v[214:217], v[10:13]
	s_setprio 0
	s_setprio 1
	v_mfma_f32_16x16x32_bf16 v[54:57], v[146:149], v[162:165], v[54:57]
	v_mfma_f32_16x16x32_bf16 v[50:53], v[154:157], v[162:165], v[50:53]
	v_mfma_f32_16x16x32_bf16 v[38:41], v[146:149], v[170:173], v[38:41]
	v_mfma_f32_16x16x32_bf16 v[34:37], v[154:157], v[170:173], v[34:37]
	v_mfma_f32_16x16x32_bf16 v[22:25], v[146:149], v[202:205], v[22:25]
	v_mfma_f32_16x16x32_bf16 v[18:21], v[154:157], v[202:205], v[18:21]
	v_mfma_f32_16x16x32_bf16 v[6:9], v[146:149], v[210:213], v[6:9]
	v_mfma_f32_16x16x32_bf16 v[2:5], v[154:157], v[210:213], v[2:5]
	v_mfma_f32_16x16x32_bf16 v[54:57], v[150:153], v[166:169], v[54:57]
	v_mfma_f32_16x16x32_bf16 v[50:53], v[158:161], v[166:169], v[50:53]
	v_mfma_f32_16x16x32_bf16 v[38:41], v[150:153], v[174:177], v[38:41]
	v_mfma_f32_16x16x32_bf16 v[34:37], v[158:161], v[174:177], v[34:37]
	v_mfma_f32_16x16x32_bf16 v[22:25], v[150:153], v[206:209], v[22:25]
	v_mfma_f32_16x16x32_bf16 v[18:21], v[158:161], v[206:209], v[18:21]
	v_mfma_f32_16x16x32_bf16 v[6:9], v[150:153], v[214:217], v[6:9]
	v_mfma_f32_16x16x32_bf16 v[2:5], v[158:161], v[214:217], v[2:5]
	s_setprio 0
	s_barrier
	s_add_i32 s37, 0, 0x18000
	s_add_i32 s56, 0, 0x1c000
	v_add_u32_e32 v142, s37, v196
	v_add_u32_e32 v158, s56, v196
	ds_read_b128 v[130:133], v142
	ds_read_b128 v[134:137], v142 offset:1024
	ds_read_b128 v[138:141], v142 offset:2048
	ds_read_b128 v[142:145], v142 offset:3072
	ds_read_b128 v[146:149], v158
	ds_read_b128 v[150:153], v158 offset:1024
	ds_read_b128 v[154:157], v158 offset:2048
	ds_read_b128 v[158:161], v158 offset:3072
	s_add_u32 s30, s30, 0x80000
	s_addc_u32 s31, s31, 0
	s_mov_b32 m0, s41
	v_lshl_add_u64 v[224:225], s[30:31], 0, v[178:179]
	ds_read_b128 v[162:165], v199 offset:32768
	ds_read_b128 v[166:169], v199 offset:33792
	ds_read_b128 v[170:173], v199 offset:34816
	ds_read_b128 v[174:177], v199 offset:35840
	ds_read_b128 v[202:205], v199 offset:36864
	ds_read_b128 v[206:209], v199 offset:37888
	ds_read_b128 v[210:213], v199 offset:38912
	ds_read_b128 v[214:217], v199 offset:39936
	global_load_lds_dwordx4 v[224:225], off
	v_lshl_add_u64 v[224:225], s[30:31], 0, v[180:181]
	s_mov_b32 m0, s42
	s_nop 0
	global_load_lds_dwordx4 v[224:225], off
	s_waitcnt vmcnt(8)
	s_waitcnt lgkmcnt(0)
	s_barrier
	s_setprio 1
	s_waitcnt lgkmcnt(0)
	v_mfma_f32_16x16x32_bf16 v[126:129], v[130:133], v[162:165], v[126:129]
	v_mfma_f32_16x16x32_bf16 v[122:125], v[138:141], v[162:165], v[122:125]
	v_mfma_f32_16x16x32_bf16 v[110:113], v[130:133], v[170:173], v[110:113]
	v_mfma_f32_16x16x32_bf16 v[106:109], v[138:141], v[170:173], v[106:109]
	v_mfma_f32_16x16x32_bf16 v[94:97], v[130:133], v[202:205], v[94:97]
	v_mfma_f32_16x16x32_bf16 v[90:93], v[138:141], v[202:205], v[90:93]
	v_mfma_f32_16x16x32_bf16 v[78:81], v[130:133], v[210:213], v[78:81]
	v_mfma_f32_16x16x32_bf16 v[74:77], v[138:141], v[210:213], v[74:77]
	v_mfma_f32_16x16x32_bf16 v[126:129], v[134:137], v[166:169], v[126:129]
	v_mfma_f32_16x16x32_bf16 v[122:125], v[142:145], v[166:169], v[122:125]
	v_mfma_f32_16x16x32_bf16 v[110:113], v[134:137], v[174:177], v[110:113]
	v_mfma_f32_16x16x32_bf16 v[106:109], v[142:145], v[174:177], v[106:109]
	v_mfma_f32_16x16x32_bf16 v[94:97], v[134:137], v[206:209], v[94:97]
	v_mfma_f32_16x16x32_bf16 v[90:93], v[142:145], v[206:209], v[90:93]
	v_mfma_f32_16x16x32_bf16 v[78:81], v[134:137], v[214:217], v[78:81]
	v_mfma_f32_16x16x32_bf16 v[74:77], v[142:145], v[214:217], v[74:77]
	s_setprio 0
	s_setprio 1
	v_mfma_f32_16x16x32_bf16 v[118:121], v[146:149], v[162:165], v[118:121]
	v_mfma_f32_16x16x32_bf16 v[114:117], v[154:157], v[162:165], v[114:117]
	v_mfma_f32_16x16x32_bf16 v[102:105], v[146:149], v[170:173], v[102:105]
	v_mfma_f32_16x16x32_bf16 v[98:101], v[154:157], v[170:173], v[98:101]
	v_mfma_f32_16x16x32_bf16 v[86:89], v[146:149], v[202:205], v[86:89]
	v_mfma_f32_16x16x32_bf16 v[82:85], v[154:157], v[202:205], v[82:85]
	v_mfma_f32_16x16x32_bf16 v[70:73], v[146:149], v[210:213], v[70:73]
	v_mfma_f32_16x16x32_bf16 v[66:69], v[154:157], v[210:213], v[66:69]
	v_mfma_f32_16x16x32_bf16 v[118:121], v[150:153], v[166:169], v[118:121]
	v_mfma_f32_16x16x32_bf16 v[114:117], v[158:161], v[166:169], v[114:117]
	v_mfma_f32_16x16x32_bf16 v[102:105], v[150:153], v[174:177], v[102:105]
	v_mfma_f32_16x16x32_bf16 v[98:101], v[158:161], v[174:177], v[98:101]
	v_mfma_f32_16x16x32_bf16 v[86:89], v[150:153], v[206:209], v[86:89]
	v_mfma_f32_16x16x32_bf16 v[82:85], v[158:161], v[206:209], v[82:85]
	v_mfma_f32_16x16x32_bf16 v[70:73], v[150:153], v[214:217], v[70:73]
	v_mfma_f32_16x16x32_bf16 v[66:69], v[158:161], v[214:217], v[66:69]
	s_setprio 0
	s_barrier
	s_add_i32 s30, s37, s38
	v_lshl_add_u64 v[194:195], v[194:195], 0, s[14:15]
	s_mov_b32 m0, s30
	ds_read_b128 v[162:165], v199 offset:49152
	ds_read_b128 v[166:169], v199 offset:50176
	ds_read_b128 v[170:173], v199 offset:51200
	ds_read_b128 v[174:177], v199 offset:52224
	ds_read_b128 v[202:205], v199 offset:53248
	ds_read_b128 v[206:209], v199 offset:54272
	ds_read_b128 v[210:213], v199 offset:55296
	ds_read_b128 v[214:217], v199 offset:56320
	global_load_lds_dwordx4 v[194:195], off
	s_add_i32 m0, s30, 0x2000
	s_add_u32 s28, s28, 0x80080
	v_lshl_add_u64 v[194:195], v[218:219], 0, s[14:15]
	s_addc_u32 s29, s29, 0
	s_add_i32 s30, s56, s38
	global_load_lds_dwordx4 v[194:195], off
	v_lshl_add_u64 v[194:195], s[28:29], 0, v[178:179]
	s_mov_b32 m0, s30
	s_nop 0
	global_load_lds_dwordx4 v[194:195], off
	v_lshl_add_u64 v[194:195], s[28:29], 0, v[180:181]
	s_add_i32 m0, s30, 0x2000
	s_nop 0
	global_load_lds_dwordx4 v[194:195], off
	v_lshl_add_u64 v[194:195], v[220:221], 0, s[14:15]
	s_mov_b32 m0, s46
	s_nop 0
	global_load_lds_dwordx4 v[194:195], off
	v_lshl_add_u64 v[194:195], v[222:223], 0, s[14:15]
	s_mov_b32 m0, s47
	s_nop 0
	global_load_lds_dwordx4 v[194:195], off
	s_waitcnt vmcnt(8)
	s_waitcnt lgkmcnt(0)
	s_barrier
	s_setprio 1
	s_waitcnt lgkmcnt(0)
	v_mfma_f32_16x16x32_bf16 v[62:65], v[130:133], v[162:165], v[62:65]
	v_mfma_f32_16x16x32_bf16 v[58:61], v[138:141], v[162:165], v[58:61]
	v_mfma_f32_16x16x32_bf16 v[46:49], v[130:133], v[170:173], v[46:49]
	v_mfma_f32_16x16x32_bf16 v[42:45], v[138:141], v[170:173], v[42:45]
	v_mfma_f32_16x16x32_bf16 v[30:33], v[130:133], v[202:205], v[30:33]
	v_mfma_f32_16x16x32_bf16 v[26:29], v[138:141], v[202:205], v[26:29]
	v_mfma_f32_16x16x32_bf16 v[14:17], v[130:133], v[210:213], v[14:17]
	v_mfma_f32_16x16x32_bf16 v[10:13], v[138:141], v[210:213], v[10:13]
	v_mfma_f32_16x16x32_bf16 v[62:65], v[134:137], v[166:169], v[62:65]
	v_mfma_f32_16x16x32_bf16 v[58:61], v[142:145], v[166:169], v[58:61]
	v_mfma_f32_16x16x32_bf16 v[46:49], v[134:137], v[174:177], v[46:49]
	v_mfma_f32_16x16x32_bf16 v[42:45], v[142:145], v[174:177], v[42:45]
	v_mfma_f32_16x16x32_bf16 v[30:33], v[134:137], v[206:209], v[30:33]
	v_mfma_f32_16x16x32_bf16 v[26:29], v[142:145], v[206:209], v[26:29]
	v_mfma_f32_16x16x32_bf16 v[14:17], v[134:137], v[214:217], v[14:17]
	v_mfma_f32_16x16x32_bf16 v[10:13], v[142:145], v[214:217], v[10:13]
	s_setprio 0
	s_setprio 1
	v_mfma_f32_16x16x32_bf16 v[54:57], v[146:149], v[162:165], v[54:57]
	v_mfma_f32_16x16x32_bf16 v[50:53], v[154:157], v[162:165], v[50:53]
	v_mfma_f32_16x16x32_bf16 v[38:41], v[146:149], v[170:173], v[38:41]
	v_mfma_f32_16x16x32_bf16 v[34:37], v[154:157], v[170:173], v[34:37]
	v_mfma_f32_16x16x32_bf16 v[22:25], v[146:149], v[202:205], v[22:25]
	v_mfma_f32_16x16x32_bf16 v[18:21], v[154:157], v[202:205], v[18:21]
	v_mfma_f32_16x16x32_bf16 v[6:9], v[146:149], v[210:213], v[6:9]
	v_mfma_f32_16x16x32_bf16 v[2:5], v[154:157], v[210:213], v[2:5]
	v_mfma_f32_16x16x32_bf16 v[54:57], v[150:153], v[166:169], v[54:57]
	v_mfma_f32_16x16x32_bf16 v[50:53], v[158:161], v[166:169], v[50:53]
	v_mfma_f32_16x16x32_bf16 v[38:41], v[150:153], v[174:177], v[38:41]
	v_mfma_f32_16x16x32_bf16 v[34:37], v[158:161], v[174:177], v[34:37]
	v_mfma_f32_16x16x32_bf16 v[22:25], v[150:153], v[206:209], v[22:25]
	v_mfma_f32_16x16x32_bf16 v[18:21], v[158:161], v[206:209], v[18:21]
	v_mfma_f32_16x16x32_bf16 v[6:9], v[150:153], v[214:217], v[6:9]
	v_mfma_f32_16x16x32_bf16 v[2:5], v[158:161], v[214:217], v[2:5]
	s_setprio 0
	s_barrier
	s_add_i32 s36, s36, 2
	s_add_u32 s10, s10, 0x100
	s_addc_u32 s11, s11, 0
	s_add_u32 s34, s34, 0x100
	s_addc_u32 s35, s35, 0
	s_cmp_gt_u32 s36, 29
	s_cbranch_scc0 .LBB0_2207
	s_mov_b32 s32, 1
	s_and_b64 vcc, exec, s[16:17]
	s_cbranch_vccz .LBB0_2210
	s_barrier

.LBB0_3094:
	v_readlane_b32 s2, v254, 5
	v_readlane_b32 s3, v254, 6
	s_cmp_lt_i32 s2, 12
	s_cselect_b64 s[2:3], -1, 0
	s_and_b64 s[2:3], s[2:3], s[0:1]
	s_andn2_b64 vcc, exec, s[2:3]
	s_cbranch_vccnz .LBB0_3137
	s_mov_b32 s32, 0
	s_waitcnt vmcnt(5)
	v_mov_b32_e32 v10, v0
	s_cmpk_lt_i32 s86, 0x200
	s_cselect_b64 s[0:1], -1, 0
	s_cmpk_gt_i32 s86, 0x1ff
	v_readfirstlane_b32 s14, v10
	s_cbranch_scc1 .LBB0_3101
	s_ashr_i32 s4, s86, 31
	s_lshr_b32 s4, s4, 29
	s_add_i32 s6, s86, s4
	s_and_b32 s4, s6, -8
	s_sub_i32 s7, s86, s4
	s_cmp_gt_i32 s7, -1
	s_cbranch_scc0 .LBB0_3098
	s_lshl_b32 s8, s7, 6
	s_cbranch_execz .LBB0_3099
	s_branch .LBB0_3100

.LBB0_3114:
	ds_read_b128 v[142:145], v148
	ds_read_b128 v[152:155], v148 offset:1024
	ds_read_b128 v[156:159], v148 offset:2048
	ds_read_b128 v[160:163], v148 offset:3072
	ds_read_b128 v[164:167], v149
	ds_read_b128 v[168:171], v149 offset:1024
	ds_read_b128 v[172:175], v149 offset:2048
	ds_read_b128 v[176:179], v149 offset:3072
	s_add_u32 s26, s24, 0x100
	s_addc_u32 s27, s25, 0
	s_cmp_eq_u32 s55, 28
	s_cselect_b32 s31, s19, s27
	s_cselect_b32 s30, s51, s26
	s_cselect_b32 s29, s17, s54
	s_cselect_b32 s28, s52, s53
	v_lshl_add_u64 v[212:213], s[24:25], 0, v[134:135]
	s_add_i32 m0, s5, 0xc000
	ds_read_b128 v[180:183], v150
	ds_read_b128 v[184:187], v150 offset:1024
	ds_read_b128 v[188:191], v150 offset:2048
	ds_read_b128 v[192:195], v150 offset:3072
	ds_read_b128 v[196:199], v150 offset:4096
	ds_read_b128 v[200:203], v150 offset:5120
	ds_read_b128 v[204:207], v150 offset:6144
	ds_read_b128 v[208:211], v150 offset:7168
	global_load_lds_dwordx4 v[212:213], off
	v_lshl_add_u64 v[212:213], s[24:25], 0, v[136:137]
	s_add_i32 m0, s5, 0xe000
	s_nop 0
	global_load_lds_dwordx4 v[212:213], off
	s_cmp_lg_u32 s32, 0
	s_cbranch_scc1 .Lkw_P11_1
	s_waitcnt vmcnt(8)
.Lkw_P11_1:
	s_waitcnt lgkmcnt(0)
	s_barrier
	s_setprio 1
	s_waitcnt lgkmcnt(0)
	v_mfma_f32_16x16x32_bf16 v[126:129], v[142:145], v[180:183], v[126:129]
	v_mfma_f32_16x16x32_bf16 v[122:125], v[156:159], v[180:183], v[122:125]
	v_mfma_f32_16x16x32_bf16 v[110:113], v[142:145], v[188:191], v[110:113]
	v_mfma_f32_16x16x32_bf16 v[106:109], v[156:159], v[188:191], v[106:109]
	v_mfma_f32_16x16x32_bf16 v[94:97], v[142:145], v[196:199], v[94:97]
	v_mfma_f32_16x16x32_bf16 v[90:93], v[156:159], v[196:199], v[90:93]
	v_mfma_f32_16x16x32_bf16 v[78:81], v[142:145], v[204:207], v[78:81]
	v_mfma_f32_16x16x32_bf16 v[74:77], v[156:159], v[204:207], v[74:77]
	v_mfma_f32_16x16x32_bf16 v[126:129], v[152:155], v[184:187], v[126:129]
	v_mfma_f32_16x16x32_bf16 v[122:125], v[160:163], v[184:187], v[122:125]
	v_mfma_f32_16x16x32_bf16 v[110:113], v[152:155], v[192:195], v[110:113]
	v_mfma_f32_16x16x32_bf16 v[106:109], v[160:163], v[192:195], v[106:109]
	v_mfma_f32_16x16x32_bf16 v[94:97], v[152:155], v[200:203], v[94:97]
	v_mfma_f32_16x16x32_bf16 v[90:93], v[160:163], v[200:203], v[90:93]
	v_mfma_f32_16x16x32_bf16 v[78:81], v[152:155], v[208:211], v[78:81]
	v_mfma_f32_16x16x32_bf16 v[74:77], v[160:163], v[208:211], v[74:77]
	s_setprio 0
	s_setprio 1
	v_mfma_f32_16x16x32_bf16 v[118:121], v[164:167], v[180:183], v[118:121]
	v_mfma_f32_16x16x32_bf16 v[114:117], v[172:175], v[180:183], v[114:117]
	v_mfma_f32_16x16x32_bf16 v[102:105], v[164:167], v[188:191], v[102:105]
	v_mfma_f32_16x16x32_bf16 v[98:101], v[172:175], v[188:191], v[98:101]
	v_mfma_f32_16x16x32_bf16 v[86:89], v[164:167], v[196:199], v[86:89]
	v_mfma_f32_16x16x32_bf16 v[82:85], v[172:175], v[196:199], v[82:85]
	v_mfma_f32_16x16x32_bf16 v[70:73], v[164:167], v[204:207], v[70:73]
	v_mfma_f32_16x16x32_bf16 v[66:69], v[172:175], v[204:207], v[66:69]
	v_mfma_f32_16x16x32_bf16 v[118:121], v[168:171], v[184:187], v[118:121]
	v_mfma_f32_16x16x32_bf16 v[114:117], v[176:179], v[184:187], v[114:117]
	v_mfma_f32_16x16x32_bf16 v[102:105], v[168:171], v[192:195], v[102:105]
	v_mfma_f32_16x16x32_bf16 v[98:101], v[176:179], v[192:195], v[98:101]
	v_mfma_f32_16x16x32_bf16 v[86:89], v[168:171], v[200:203], v[86:89]
	v_mfma_f32_16x16x32_bf16 v[82:85], v[176:179], v[200:203], v[82:85]
	v_mfma_f32_16x16x32_bf16 v[70:73], v[168:171], v[208:211], v[70:73]
	v_mfma_f32_16x16x32_bf16 v[66:69], v[176:179], v[208:211], v[66:69]
	s_setprio 0
	s_barrier
	s_add_i32 s24, s48, s37
	v_lshl_add_u64 v[212:213], s[28:29], 0, v[130:131]
	s_mov_b32 m0, s24
	ds_read_b128 v[180:183], v150 offset:16384
	ds_read_b128 v[184:187], v150 offset:17408
	ds_read_b128 v[188:191], v150 offset:18432
	ds_read_b128 v[192:195], v150 offset:19456
	ds_read_b128 v[196:199], v150 offset:20480
	ds_read_b128 v[200:203], v150 offset:21504
	ds_read_b128 v[204:207], v150 offset:22528
	ds_read_b128 v[208:211], v150 offset:23552
	global_load_lds_dwordx4 v[212:213], off
	s_add_i32 m0, s24, 0x2000
	s_add_u32 s24, s28, 0x80000
	v_lshl_add_u64 v[214:215], s[28:29], 0, v[132:133]
	s_addc_u32 s25, s29, 0
	s_add_i32 s56, s49, s37
	global_load_lds_dwordx4 v[214:215], off
	v_lshl_add_u64 v[216:217], s[24:25], 0, v[130:131]
	s_mov_b32 m0, s56
	v_lshl_add_u64 v[218:219], s[30:31], 0, v[132:133]
	global_load_lds_dwordx4 v[216:217], off
	v_lshl_add_u64 v[216:217], s[24:25], 0, v[132:133]
	s_add_i32 m0, s56, 0x2000
	s_nop 0
	global_load_lds_dwordx4 v[216:217], off
	v_lshl_add_u64 v[216:217], s[30:31], 0, v[130:131]
	s_mov_b32 m0, s5
	s_nop 0
	global_load_lds_dwordx4 v[216:217], off
	s_mov_b32 m0, s38
	s_nop 0
	global_load_lds_dwordx4 v[218:219], off
	s_cmp_lg_u32 s32, 0
	s_cbranch_scc1 .Lkw_P11_2
	s_waitcnt vmcnt(8)
.Lkw_P11_2:
	s_mov_b32 s32, 0
	s_waitcnt lgkmcnt(0)
	s_barrier
	s_setprio 1
	s_waitcnt lgkmcnt(0)
	v_mfma_f32_16x16x32_bf16 v[62:65], v[142:145], v[180:183], v[62:65]
	v_mfma_f32_16x16x32_bf16 v[58:61], v[156:159], v[180:183], v[58:61]
	v_mfma_f32_16x16x32_bf16 v[46:49], v[142:145], v[188:191], v[46:49]
	v_mfma_f32_16x16x32_bf16 v[42:45], v[156:159], v[188:191], v[42:45]
	v_mfma_f32_16x16x32_bf16 v[30:33], v[142:145], v[196:199], v[30:33]
	v_mfma_f32_16x16x32_bf16 v[26:29], v[156:159], v[196:199], v[26:29]
	v_mfma_f32_16x16x32_bf16 v[14:17], v[142:145], v[204:207], v[14:17]
	v_mfma_f32_16x16x32_bf16 v[10:13], v[156:159], v[204:207], v[10:13]
	v_mfma_f32_16x16x32_bf16 v[62:65], v[152:155], v[184:187], v[62:65]
	v_mfma_f32_16x16x32_bf16 v[58:61], v[160:163], v[184:187], v[58:61]
	v_mfma_f32_16x16x32_bf16 v[46:49], v[152:155], v[192:195], v[46:49]
	v_mfma_f32_16x16x32_bf16 v[42:45], v[160:163], v[192:195], v[42:45]
	v_mfma_f32_16x16x32_bf16 v[30:33], v[152:155], v[200:203], v[30:33]
	v_mfma_f32_16x16x32_bf16 v[26:29], v[160:163], v[200:203], v[26:29]
	v_mfma_f32_16x16x32_bf16 v[14:17], v[152:155], v[208:211], v[14:17]
	v_mfma_f32_16x16x32_bf16 v[10:13], v[160:163], v[208:211], v[10:13]
	s_setprio 0
	s_setprio 1
	v_mfma_f32_16x16x32_bf16 v[54:57], v[164:167], v[180:183], v[54:57]
	v_mfma_f32_16x16x32_bf16 v[50:53], v[172:175], v[180:183], v[50:53]
	v_mfma_f32_16x16x32_bf16 v[38:41], v[164:167], v[188:191], v[38:41]
	v_mfma_f32_16x16x32_bf16 v[34:37], v[172:175], v[188:191], v[34:37]
	v_mfma_f32_16x16x32_bf16 v[22:25], v[164:167], v[196:199], v[22:25]
	v_mfma_f32_16x16x32_bf16 v[18:21], v[172:175], v[196:199], v[18:21]
	v_mfma_f32_16x16x32_bf16 v[6:9], v[164:167], v[204:207], v[6:9]
	v_mfma_f32_16x16x32_bf16 v[2:5], v[172:175], v[204:207], v[2:5]
	v_mfma_f32_16x16x32_bf16 v[54:57], v[168:171], v[184:187], v[54:57]
	v_mfma_f32_16x16x32_bf16 v[50:53], v[176:179], v[184:187], v[50:53]
	v_mfma_f32_16x16x32_bf16 v[38:41], v[168:171], v[192:195], v[38:41]
	v_mfma_f32_16x16x32_bf16 v[34:37], v[176:179], v[192:195], v[34:37]
	v_mfma_f32_16x16x32_bf16 v[22:25], v[168:171], v[200:203], v[22:25]
	v_mfma_f32_16x16x32_bf16 v[18:21], v[176:179], v[200:203], v[18:21]
	v_mfma_f32_16x16x32_bf16 v[6:9], v[168:171], v[208:211], v[6:9]
	v_mfma_f32_16x16x32_bf16 v[2:5], v[176:179], v[208:211], v[2:5]
	s_setprio 0
	s_barrier
	s_add_i32 s56, 0, 0x18000
	s_add_i32 s57, 0, 0x1c000
	v_add_u32_e32 v160, s56, v147
	v_add_u32_e32 v176, s57, v147
	ds_read_b128 v[142:145], v160
	ds_read_b128 v[152:155], v160 offset:1024
	ds_read_b128 v[156:159], v160 offset:2048
	ds_read_b128 v[160:163], v160 offset:3072
	ds_read_b128 v[164:167], v176
	ds_read_b128 v[168:171], v176 offset:1024
	ds_read_b128 v[172:175], v176 offset:2048
	ds_read_b128 v[176:179], v176 offset:3072
	s_add_u32 s24, s30, 0x80000
	s_addc_u32 s25, s31, 0
	s_mov_b32 m0, s39
	v_lshl_add_u64 v[220:221], s[24:25], 0, v[130:131]
	ds_read_b128 v[180:183], v150 offset:32768
	ds_read_b128 v[184:187], v150 offset:33792
	ds_read_b128 v[188:191], v150 offset:34816
	ds_read_b128 v[192:195], v150 offset:35840
	ds_read_b128 v[196:199], v150 offset:36864
	ds_read_b128 v[200:203], v150 offset:37888
	ds_read_b128 v[204:207], v150 offset:38912
	ds_read_b128 v[208:211], v150 offset:39936
	global_load_lds_dwordx4 v[220:221], off
	v_lshl_add_u64 v[220:221], s[24:25], 0, v[132:133]
	s_mov_b32 m0, s40
	s_nop 0
	global_load_lds_dwordx4 v[220:221], off
	s_waitcnt vmcnt(8)
	s_waitcnt lgkmcnt(0)
	s_barrier
	s_setprio 1
	s_waitcnt lgkmcnt(0)
	v_mfma_f32_16x16x32_bf16 v[126:129], v[142:145], v[180:183], v[126:129]
	v_mfma_f32_16x16x32_bf16 v[122:125], v[156:159], v[180:183], v[122:125]
	v_mfma_f32_16x16x32_bf16 v[110:113], v[142:145], v[188:191], v[110:113]
	v_mfma_f32_16x16x32_bf16 v[106:109], v[156:159], v[188:191], v[106:109]
	v_mfma_f32_16x16x32_bf16 v[94:97], v[142:145], v[196:199], v[94:97]
	v_mfma_f32_16x16x32_bf16 v[90:93], v[156:159], v[196:199], v[90:93]
	v_mfma_f32_16x16x32_bf16 v[78:81], v[142:145], v[204:207], v[78:81]
	v_mfma_f32_16x16x32_bf16 v[74:77], v[156:159], v[204:207], v[74:77]
	v_mfma_f32_16x16x32_bf16 v[126:129], v[152:155], v[184:187], v[126:129]
	v_mfma_f32_16x16x32_bf16 v[122:125], v[160:163], v[184:187], v[122:125]
	v_mfma_f32_16x16x32_bf16 v[110:113], v[152:155], v[192:195], v[110:113]
	v_mfma_f32_16x16x32_bf16 v[106:109], v[160:163], v[192:195], v[106:109]
	v_mfma_f32_16x16x32_bf16 v[94:97], v[152:155], v[200:203], v[94:97]
	v_mfma_f32_16x16x32_bf16 v[90:93], v[160:163], v[200:203], v[90:93]
	v_mfma_f32_16x16x32_bf16 v[78:81], v[152:155], v[208:211], v[78:81]
	v_mfma_f32_16x16x32_bf16 v[74:77], v[160:163], v[208:211], v[74:77]
	s_setprio 0
	s_setprio 1
	v_mfma_f32_16x16x32_bf16 v[118:121], v[164:167], v[180:183], v[118:121]
	v_mfma_f32_16x16x32_bf16 v[114:117], v[172:175], v[180:183], v[114:117]
	v_mfma_f32_16x16x32_bf16 v[102:105], v[164:167], v[188:191], v[102:105]
	v_mfma_f32_16x16x32_bf16 v[98:101], v[172:175], v[188:191], v[98:101]
	v_mfma_f32_16x16x32_bf16 v[86:89], v[164:167], v[196:199], v[86:89]
	v_mfma_f32_16x16x32_bf16 v[82:85], v[172:175], v[196:199], v[82:85]
	v_mfma_f32_16x16x32_bf16 v[70:73], v[164:167], v[204:207], v[70:73]
	v_mfma_f32_16x16x32_bf16 v[66:69], v[172:175], v[204:207], v[66:69]
	v_mfma_f32_16x16x32_bf16 v[118:121], v[168:171], v[184:187], v[118:121]
	v_mfma_f32_16x16x32_bf16 v[114:117], v[176:179], v[184:187], v[114:117]
	v_mfma_f32_16x16x32_bf16 v[102:105], v[168:171], v[192:195], v[102:105]
	v_mfma_f32_16x16x32_bf16 v[98:101], v[176:179], v[192:195], v[98:101]
	v_mfma_f32_16x16x32_bf16 v[86:89], v[168:171], v[200:203], v[86:89]
	v_mfma_f32_16x16x32_bf16 v[82:85], v[176:179], v[200:203], v[82:85]
	v_mfma_f32_16x16x32_bf16 v[70:73], v[168:171], v[208:211], v[70:73]
	v_mfma_f32_16x16x32_bf16 v[66:69], v[176:179], v[208:211], v[66:69]
	s_setprio 0
	s_barrier
	s_add_i32 s24, s56, s37
	v_lshl_add_u64 v[212:213], v[212:213], 0, s[12:13]
	s_mov_b32 m0, s24
	ds_read_b128 v[180:183], v150 offset:49152
	ds_read_b128 v[184:187], v150 offset:50176
	ds_read_b128 v[188:191], v150 offset:51200
	ds_read_b128 v[192:195], v150 offset:52224
	ds_read_b128 v[196:199], v150 offset:53248
	ds_read_b128 v[200:203], v150 offset:54272
	ds_read_b128 v[204:207], v150 offset:55296
	ds_read_b128 v[208:211], v150 offset:56320
	global_load_lds_dwordx4 v[212:213], off
	s_add_i32 m0, s24, 0x2000
	s_add_u32 s24, s28, 0x80080
	v_lshl_add_u64 v[212:213], v[214:215], 0, s[12:13]
	s_addc_u32 s25, s29, 0
	s_add_i32 s28, s57, s37
	global_load_lds_dwordx4 v[212:213], off
	v_lshl_add_u64 v[212:213], s[24:25], 0, v[130:131]
	s_mov_b32 m0, s28
	s_nop 0
	global_load_lds_dwordx4 v[212:213], off
	v_lshl_add_u64 v[212:213], s[24:25], 0, v[132:133]
	s_add_i32 m0, s28, 0x2000
	s_nop 0
	global_load_lds_dwordx4 v[212:213], off
	v_lshl_add_u64 v[212:213], v[216:217], 0, s[12:13]
	s_mov_b32 m0, s44
	s_nop 0
	global_load_lds_dwordx4 v[212:213], off
	v_lshl_add_u64 v[212:213], v[218:219], 0, s[12:13]
	s_mov_b32 m0, s45
	s_nop 0
	global_load_lds_dwordx4 v[212:213], off
	s_waitcnt vmcnt(8)
	s_waitcnt lgkmcnt(0)
	s_barrier
	s_setprio 1
	s_waitcnt lgkmcnt(0)
	v_mfma_f32_16x16x32_bf16 v[62:65], v[142:145], v[180:183], v[62:65]
	v_mfma_f32_16x16x32_bf16 v[58:61], v[156:159], v[180:183], v[58:61]
	v_mfma_f32_16x16x32_bf16 v[46:49], v[142:145], v[188:191], v[46:49]
	v_mfma_f32_16x16x32_bf16 v[42:45], v[156:159], v[188:191], v[42:45]
	v_mfma_f32_16x16x32_bf16 v[30:33], v[142:145], v[196:199], v[30:33]
	v_mfma_f32_16x16x32_bf16 v[26:29], v[156:159], v[196:199], v[26:29]
	v_mfma_f32_16x16x32_bf16 v[14:17], v[142:145], v[204:207], v[14:17]
	v_mfma_f32_16x16x32_bf16 v[10:13], v[156:159], v[204:207], v[10:13]
	v_mfma_f32_16x16x32_bf16 v[62:65], v[152:155], v[184:187], v[62:65]
	v_mfma_f32_16x16x32_bf16 v[58:61], v[160:163], v[184:187], v[58:61]
	v_mfma_f32_16x16x32_bf16 v[46:49], v[152:155], v[192:195], v[46:49]
	v_mfma_f32_16x16x32_bf16 v[42:45], v[160:163], v[192:195], v[42:45]
	v_mfma_f32_16x16x32_bf16 v[30:33], v[152:155], v[200:203], v[30:33]
	v_mfma_f32_16x16x32_bf16 v[26:29], v[160:163], v[200:203], v[26:29]
	v_mfma_f32_16x16x32_bf16 v[14:17], v[152:155], v[208:211], v[14:17]
	v_mfma_f32_16x16x32_bf16 v[10:13], v[160:163], v[208:211], v[10:13]
	s_setprio 0
	s_setprio 1
	v_mfma_f32_16x16x32_bf16 v[54:57], v[164:167], v[180:183], v[54:57]
	v_mfma_f32_16x16x32_bf16 v[50:53], v[172:175], v[180:183], v[50:53]
	v_mfma_f32_16x16x32_bf16 v[38:41], v[164:167], v[188:191], v[38:41]
	v_mfma_f32_16x16x32_bf16 v[34:37], v[172:175], v[188:191], v[34:37]
	v_mfma_f32_16x16x32_bf16 v[22:25], v[164:167], v[196:199], v[22:25]
	v_mfma_f32_16x16x32_bf16 v[18:21], v[172:175], v[196:199], v[18:21]
	v_mfma_f32_16x16x32_bf16 v[6:9], v[164:167], v[204:207], v[6:9]
	v_mfma_f32_16x16x32_bf16 v[2:5], v[172:175], v[204:207], v[2:5]
	v_mfma_f32_16x16x32_bf16 v[54:57], v[168:171], v[184:187], v[54:57]
	v_mfma_f32_16x16x32_bf16 v[50:53], v[176:179], v[184:187], v[50:53]
	v_mfma_f32_16x16x32_bf16 v[38:41], v[168:171], v[192:195], v[38:41]
	v_mfma_f32_16x16x32_bf16 v[34:37], v[176:179], v[192:195], v[34:37]
	v_mfma_f32_16x16x32_bf16 v[22:25], v[168:171], v[200:203], v[22:25]
	v_mfma_f32_16x16x32_bf16 v[18:21], v[176:179], v[200:203], v[18:21]
	v_mfma_f32_16x16x32_bf16 v[6:9], v[168:171], v[208:211], v[6:9]
	v_mfma_f32_16x16x32_bf16 v[2:5], v[176:179], v[208:211], v[2:5]
	s_setprio 0
	s_barrier
	s_add_i32 s55, s55, 2
	s_add_u32 s53, s53, 0x100
	s_addc_u32 s54, s54, 0
	s_cmp_gt_u32 s55, 29
	s_mov_b64 s[24:25], s[26:27]
	s_cbranch_scc0 .LBB0_3114
	s_mov_b32 s32, 1
	s_and_b64 vcc, exec, s[14:15]
	s_cbranch_vccz .LBB0_3117
	s_barrier

.LBB0_3191:
	v_readlane_b32 s2, v254, 5
	v_readlane_b32 s3, v254, 6
	s_cmp_lt_i32 s2, 13
	s_cselect_b64 s[2:3], -1, 0
	s_and_b64 s[2:3], s[2:3], s[0:1]
	s_andn2_b64 vcc, exec, s[2:3]
	s_cbranch_vccnz .LBB0_3210
	s_mov_b32 s32, 0
	s_waitcnt vmcnt(5)
	v_mov_b32_e32 v11, v0
	s_cmpk_gt_i32 s86, 0xaff
	v_readfirstlane_b32 s1, v11
	s_cbranch_scc1 .LBB0_3210
	v_lshlrev_b32_e32 v1, 4, v11
	s_waitcnt vmcnt(0)
	v_add_u32_e32 v2, 0x2000, v1
	s_waitcnt lgkmcnt(0)
	v_ashrrev_i32_e32 v3, 31, v2
	v_lshrrev_b32_e32 v3, 22, v3
	v_add_u32_e32 v3, v2, v3
	v_ashrrev_i32_e32 v10, 10, v3
	v_mul_i32_i24_e32 v3, 0x400, v10
	v_sub_u32_e32 v2, v2, v3
	v_lshrrev_b32_e32 v3, 4, v2
	v_bitop3_b32 v2, v3, v2, 32 bitop3:0x6c
	v_ashrrev_i32_e32 v3, 31, v2
	v_lshrrev_b32_e32 v3, 26, v3
	v_add_u32_e32 v3, v2, v3
	v_lshlrev_b32_e32 v4, 3, v10
	v_ashrrev_i32_e32 v12, 6, v3
	v_and_b32_e32 v4, -16, v4
	v_add_u32_e32 v4, v12, v4
	v_and_b32_e32 v5, 3, v12
	s_mov_b32 s0, 0xfffe0
	v_lshrrev_b32_e32 v6, 2, v4
	v_lshlrev_b32_e32 v7, 1, v4
	v_and_b32_e32 v3, 0xc0, v3
	v_and_or_b32 v5, v4, s0, v5
	v_and_b32_e32 v6, 4, v6
	v_and_b32_e32 v7, 24, v7
	v_sub_u32_e32 v2, v2, v3
	v_mov_b32_e32 v3, 1
	v_or3_b32 v5, v5, v6, v7
	v_lshlrev_b32_e32 v6, 5, v10
	v_ashrrev_i16_sdwa v2, v3, sext(v2) dst_sel:DWORD dst_unused:UNUSED_PAD src0_sel:DWORD src1_sel:BYTE_0
	v_and_b32_e32 v6, 32, v6
	v_bfe_i32 v13, v2, 0, 16
	v_add_lshl_u32 v2, v6, v13, 1
	v_lshl_add_u32 v130, v5, 12, v2
	v_lshl_add_u32 v132, v4, 12, v2
	v_bfe_i32 v2, v11, 27, 1
	v_lshrrev_b32_e32 v2, 22, v2
	v_add_u32_e32 v2, v1, v2
	v_and_b32_e32 v2, 0xfffffc00, v2
	v_sub_u32_e32 v1, v1, v2
	v_lshrrev_b32_e32 v2, 4, v1
	v_ashrrev_i32_e32 v4, 31, v11
	v_bitop3_b32 v1, v2, v1, 32 bitop3:0x6c
	v_lshrrev_b32_e32 v4, 26, v4
	v_ashrrev_i32_e32 v2, 31, v1
	v_add_u32_e32 v4, v11, v4
	v_lshrrev_b32_e32 v2, 26, v2
	v_ashrrev_i32_e32 v15, 6, v4
	v_add_u32_e32 v2, v1, v2
	v_lshlrev_b32_e32 v4, 3, v15
	s_add_u32 s27, s92, 0xc300000
	v_ashrrev_i32_e32 v14, 6, v2
	v_and_b32_e32 v4, -16, v4
	s_addc_u32 s29, s93, 0
	v_add_u32_e32 v4, v14, v4
	v_and_b32_e32 v5, 3, v14
	s_ashr_i32 s44, s86, 31
	v_and_or_b32 v5, v4, s0, v5
	s_lshr_b32 s0, s44, 29
	s_add_i32 s0, s86, s0
	s_ashr_i32 s12, s1, 6
	s_ashr_i32 s4, s0, 3
	s_and_b32 s0, s0, -8
	s_ashr_i32 s13, s1, 8
	s_lshl_b32 s33, s12, 10
	s_sub_i32 s0, s86, s0
	s_cmp_lt_i32 s0, 0
	s_movk_i32 s45, 0x161
	s_cselect_b32 s5, s45, 0x160
	s_mul_i32 s0, s0, s5
	s_add_i32 s0, s0, s4
	s_mul_hi_i32 s4, s0, 0x2e8ba2e9
	s_lshr_b32 s5, s4, 31
	s_ashr_i32 s4, s4, 5
	s_add_i32 s4, s4, s5
	s_lshl_b32 s5, s4, 2
	s_mulk_i32 s4, 0xb0
	s_sub_i32 s4, s0, s4
	s_sext_i32_i16 s0, s4
	s_bfe_u32 s0, s0, 0x2001d
	s_add_i32 s6, s4, s0
	s_sext_i32_i16 s0, s6
	s_and_b32 s6, s6, 0xfffc
	s_sub_i32 s4, s4, s6
	s_sext_i32_i16 s4, s4
	v_lshrrev_b32_e32 v6, 2, v4
	v_lshlrev_b32_e32 v7, 1, v4
	v_and_b32_e32 v2, 0xc0, v2
	s_lshr_b32 s0, s0, 2
	s_add_i32 s6, s5, s4
	v_and_b32_e32 v6, 4, v6
	v_and_b32_e32 v7, 24, v7
	v_sub_u32_e32 v1, v1, v2
	s_ashr_i32 s7, s6, 31
	s_bfe_i64 s[8:9], s[0:1], 0x100000
	v_or3_b32 v5, v5, v6, v7
	v_lshlrev_b32_e32 v6, 5, v15
	v_ashrrev_i16_sdwa v1, v3, sext(v1) dst_sel:DWORD dst_unused:UNUSED_PAD src0_sel:DWORD src1_sel:BYTE_0
	s_lshl_b64 s[4:5], s[6:7], 20
	s_lshl_b64 s[8:9], s[8:9], 20
	v_and_b32_e32 v6, 32, v6
	v_bfe_i32 v16, v1, 0, 16
	s_add_u32 s40, s27, s8
	v_add_lshl_u32 v1, v6, v16, 1
	s_addc_u32 s41, s29, s9
	s_add_i32 s46, s33, 0
	v_lshl_add_u32 v134, v5, 12, v1
	s_add_i32 m0, s46, 0x10000
	v_lshl_add_u32 v136, v4, 12, v1
	global_load_lds_dwordx4 v134, s[40:41]
	s_add_i32 m0, s46, 0x12000
	s_add_u32 s8, s40, 0x80000
	global_load_lds_dwordx4 v130, s[40:41]
	s_addc_u32 s9, s41, 0
	s_add_i32 m0, s46, 0x14000
	v_mov_b32_e32 v135, 0
	global_load_lds_dwordx4 v134, s[8:9]
	s_add_i32 m0, s46, 0x16000
	v_mov_b32_e32 v131, v135
	global_load_lds_dwordx4 v130, s[8:9]
	s_add_u32 s8, s88, s4
	s_addc_u32 s9, s89, s5
	s_add_i32 s47, s46, 0x2000
	s_mov_b32 m0, s46
	s_add_u32 s4, s8, 0x80000
	global_load_lds_dwordx4 v136, s[8:9]
	s_mov_b32 m0, s47
	s_addc_u32 s5, s9, 0
	s_add_i32 s48, s46, 0x4000
	global_load_lds_dwordx4 v132, s[8:9]
	s_mov_b32 m0, s48
	s_add_i32 s49, s46, 0x6000
	global_load_lds_dwordx4 v136, s[4:5]
	s_mov_b32 m0, s49
	v_mov_b32_e32 v137, v135
	global_load_lds_dwordx4 v132, s[4:5]
	v_mov_b32_e32 v133, v135
	s_cmp_eq_u32 s13, 1
	s_mov_b32 s50, 0
	v_lshl_add_u64 v[8:9], s[40:41], 0, v[134:135]
	v_lshl_add_u64 v[4:5], s[40:41], 0, v[130:131]
	v_lshl_add_u64 v[2:3], s[8:9], 0, v[136:137]
	s_cselect_b64 s[4:5], -1, 0
	s_cmp_lg_u32 s13, 1
	v_lshl_add_u64 v[6:7], s[8:9], 0, v[132:133]
	s_cbranch_scc1 .LBB0_3195
	s_barrier

.LBB0_3201:
	ds_read_b128 v[146:149], v164
	s_waitcnt lgkmcnt(0)
	ds_read_b128 v[150:153], v164 offset:1024
	ds_read_b128 v[154:157], v164 offset:2048
	ds_read_b128 v[158:161], v164 offset:3072
	ds_read_b128 v[168:171], v165
	ds_read_b128 v[172:175], v165 offset:1024
	ds_read_b128 v[176:179], v165 offset:2048
	ds_read_b128 v[180:183], v165 offset:3072
	s_add_u32 s40, s8, 0xfff80080
	s_addc_u32 s41, s9, -1
	s_cmp_eq_u32 s66, 28
	s_cselect_b32 s43, s7, s41
	s_cselect_b32 s42, s35, s40
	s_cselect_b32 s41, s31, s65
	s_cselect_b32 s40, s63, s64
	v_lshl_add_u64 v[216:217], s[8:9], 0, v[138:139]
	s_add_i32 m0, s46, 0xc000
	ds_read_b128 v[184:187], v166
	ds_read_b128 v[188:191], v166 offset:1024
	ds_read_b128 v[192:195], v166 offset:2048
	ds_read_b128 v[196:199], v166 offset:3072
	ds_read_b128 v[200:203], v166 offset:4096
	ds_read_b128 v[204:207], v166 offset:5120
	ds_read_b128 v[208:211], v166 offset:6144
	ds_read_b128 v[212:215], v166 offset:7168
	global_load_lds_dwordx4 v[216:217], off
	v_lshl_add_u64 v[216:217], s[8:9], 0, v[140:141]
	s_add_i32 m0, s46, 0xe000
	s_nop 0
	global_load_lds_dwordx4 v[216:217], off
	s_cmp_lg_u32 s32, 0
	s_cbranch_scc1 .Lkw_P12_1
	s_waitcnt vmcnt(8)
.Lkw_P12_1:
	s_waitcnt lgkmcnt(0)
	s_barrier
	s_setprio 1
	s_waitcnt lgkmcnt(0)
	v_mfma_f32_16x16x32_bf16 v[126:129], v[146:149], v[184:187], v[126:129]
	v_mfma_f32_16x16x32_bf16 v[122:125], v[154:157], v[184:187], v[122:125]
	v_mfma_f32_16x16x32_bf16 v[118:121], v[146:149], v[192:195], v[118:121]
	v_mfma_f32_16x16x32_bf16 v[110:113], v[154:157], v[192:195], v[110:113]
	v_mfma_f32_16x16x32_bf16 v[102:105], v[146:149], v[200:203], v[102:105]
	v_mfma_f32_16x16x32_bf16 v[94:97], v[154:157], v[200:203], v[94:97]
	v_mfma_f32_16x16x32_bf16 v[86:89], v[146:149], v[208:211], v[86:89]
	v_mfma_f32_16x16x32_bf16 v[78:81], v[154:157], v[208:211], v[78:81]
	v_mfma_f32_16x16x32_bf16 v[126:129], v[150:153], v[188:191], v[126:129]
	v_mfma_f32_16x16x32_bf16 v[122:125], v[158:161], v[188:191], v[122:125]
	v_mfma_f32_16x16x32_bf16 v[118:121], v[150:153], v[196:199], v[118:121]
	v_mfma_f32_16x16x32_bf16 v[110:113], v[158:161], v[196:199], v[110:113]
	v_mfma_f32_16x16x32_bf16 v[102:105], v[150:153], v[204:207], v[102:105]
	v_mfma_f32_16x16x32_bf16 v[94:97], v[158:161], v[204:207], v[94:97]
	v_mfma_f32_16x16x32_bf16 v[86:89], v[150:153], v[212:215], v[86:89]
	v_mfma_f32_16x16x32_bf16 v[78:81], v[158:161], v[212:215], v[78:81]
	s_setprio 0
	s_setprio 1
	v_mfma_f32_16x16x32_bf16 v[114:117], v[168:171], v[184:187], v[114:117]
	v_mfma_f32_16x16x32_bf16 v[106:109], v[176:179], v[184:187], v[106:109]
	v_mfma_f32_16x16x32_bf16 v[98:101], v[168:171], v[192:195], v[98:101]
	v_mfma_f32_16x16x32_bf16 v[90:93], v[176:179], v[192:195], v[90:93]
	v_mfma_f32_16x16x32_bf16 v[82:85], v[168:171], v[200:203], v[82:85]
	v_mfma_f32_16x16x32_bf16 v[74:77], v[176:179], v[200:203], v[74:77]
	v_mfma_f32_16x16x32_bf16 v[70:73], v[168:171], v[208:211], v[70:73]
	v_mfma_f32_16x16x32_bf16 v[66:69], v[176:179], v[208:211], v[66:69]
	v_mfma_f32_16x16x32_bf16 v[114:117], v[172:175], v[188:191], v[114:117]
	v_mfma_f32_16x16x32_bf16 v[106:109], v[180:183], v[188:191], v[106:109]
	v_mfma_f32_16x16x32_bf16 v[98:101], v[172:175], v[196:199], v[98:101]
	v_mfma_f32_16x16x32_bf16 v[90:93], v[180:183], v[196:199], v[90:93]
	v_mfma_f32_16x16x32_bf16 v[82:85], v[172:175], v[204:207], v[82:85]
	v_mfma_f32_16x16x32_bf16 v[74:77], v[180:183], v[204:207], v[74:77]
	v_mfma_f32_16x16x32_bf16 v[70:73], v[172:175], v[212:215], v[70:73]
	v_mfma_f32_16x16x32_bf16 v[66:69], v[180:183], v[212:215], v[66:69]
	s_setprio 0
	s_barrier
	s_add_i32 s67, s56, s33
	v_lshl_add_u64 v[216:217], s[40:41], 0, v[134:135]
	s_mov_b32 m0, s67
	ds_read_b128 v[184:187], v166 offset:16384
	ds_read_b128 v[188:191], v166 offset:17408
	ds_read_b128 v[192:195], v166 offset:18432
	ds_read_b128 v[196:199], v166 offset:19456
	ds_read_b128 v[200:203], v166 offset:20480
	ds_read_b128 v[204:207], v166 offset:21504
	ds_read_b128 v[208:211], v166 offset:22528
	ds_read_b128 v[212:215], v166 offset:23552
	global_load_lds_dwordx4 v[216:217], off
	s_add_i32 m0, s67, 0x2000
	s_add_u32 s68, s40, 0x80000
	v_lshl_add_u64 v[218:219], s[40:41], 0, v[130:131]
	s_addc_u32 s69, s41, 0
	s_add_i32 s67, s57, s33
	global_load_lds_dwordx4 v[218:219], off
	v_lshl_add_u64 v[220:221], s[68:69], 0, v[134:135]
	s_mov_b32 m0, s67
	v_lshl_add_u64 v[222:223], s[42:43], 0, v[132:133]
	global_load_lds_dwordx4 v[220:221], off
	v_lshl_add_u64 v[220:221], s[68:69], 0, v[130:131]
	s_add_i32 m0, s67, 0x2000
	s_nop 0
	global_load_lds_dwordx4 v[220:221], off
	v_lshl_add_u64 v[220:221], s[42:43], 0, v[136:137]
	s_mov_b32 m0, s46
	s_nop 0
	global_load_lds_dwordx4 v[220:221], off
	s_mov_b32 m0, s47
	s_nop 0
	global_load_lds_dwordx4 v[222:223], off
	s_cmp_lg_u32 s32, 0
	s_cbranch_scc1 .Lkw_P12_2
	s_waitcnt vmcnt(8)
.Lkw_P12_2:
	s_mov_b32 s32, 0
	s_waitcnt lgkmcnt(0)
	s_barrier
	s_setprio 1
	s_waitcnt lgkmcnt(0)
	v_mfma_f32_16x16x32_bf16 v[62:65], v[146:149], v[184:187], v[62:65]
	v_mfma_f32_16x16x32_bf16 v[58:61], v[154:157], v[184:187], v[58:61]
	v_mfma_f32_16x16x32_bf16 v[54:57], v[146:149], v[192:195], v[54:57]
	v_mfma_f32_16x16x32_bf16 v[46:49], v[154:157], v[192:195], v[46:49]
	v_mfma_f32_16x16x32_bf16 v[38:41], v[146:149], v[200:203], v[38:41]
	v_mfma_f32_16x16x32_bf16 v[30:33], v[154:157], v[200:203], v[30:33]
	v_mfma_f32_16x16x32_bf16 v[22:25], v[146:149], v[208:211], v[22:25]
	v_mfma_f32_16x16x32_bf16 v[14:17], v[154:157], v[208:211], v[14:17]
	v_mfma_f32_16x16x32_bf16 v[62:65], v[150:153], v[188:191], v[62:65]
	v_mfma_f32_16x16x32_bf16 v[58:61], v[158:161], v[188:191], v[58:61]
	v_mfma_f32_16x16x32_bf16 v[54:57], v[150:153], v[196:199], v[54:57]
	v_mfma_f32_16x16x32_bf16 v[46:49], v[158:161], v[196:199], v[46:49]
	v_mfma_f32_16x16x32_bf16 v[38:41], v[150:153], v[204:207], v[38:41]
	v_mfma_f32_16x16x32_bf16 v[30:33], v[158:161], v[204:207], v[30:33]
	v_mfma_f32_16x16x32_bf16 v[22:25], v[150:153], v[212:215], v[22:25]
	v_mfma_f32_16x16x32_bf16 v[14:17], v[158:161], v[212:215], v[14:17]
	s_setprio 0
	s_setprio 1
	v_mfma_f32_16x16x32_bf16 v[50:53], v[168:171], v[184:187], v[50:53]
	v_mfma_f32_16x16x32_bf16 v[42:45], v[176:179], v[184:187], v[42:45]
	v_mfma_f32_16x16x32_bf16 v[34:37], v[168:171], v[192:195], v[34:37]
	v_mfma_f32_16x16x32_bf16 v[26:29], v[176:179], v[192:195], v[26:29]
	v_mfma_f32_16x16x32_bf16 v[18:21], v[168:171], v[200:203], v[18:21]
	v_mfma_f32_16x16x32_bf16 v[10:13], v[176:179], v[200:203], v[10:13]
	v_mfma_f32_16x16x32_bf16 v[6:9], v[168:171], v[208:211], v[6:9]
	v_mfma_f32_16x16x32_bf16 v[2:5], v[176:179], v[208:211], v[2:5]
	v_mfma_f32_16x16x32_bf16 v[50:53], v[172:175], v[188:191], v[50:53]
	v_mfma_f32_16x16x32_bf16 v[42:45], v[180:183], v[188:191], v[42:45]
	v_mfma_f32_16x16x32_bf16 v[34:37], v[172:175], v[196:199], v[34:37]
	v_mfma_f32_16x16x32_bf16 v[26:29], v[180:183], v[196:199], v[26:29]
	v_mfma_f32_16x16x32_bf16 v[18:21], v[172:175], v[204:207], v[18:21]
	v_mfma_f32_16x16x32_bf16 v[10:13], v[180:183], v[204:207], v[10:13]
	v_mfma_f32_16x16x32_bf16 v[6:9], v[172:175], v[212:215], v[6:9]
	v_mfma_f32_16x16x32_bf16 v[2:5], v[180:183], v[212:215], v[2:5]
	s_setprio 0
	s_barrier
	s_add_i32 s67, 0, 0x18000
	s_add_i32 s68, 0, 0x1c000
	v_add_u32_e32 v158, s67, v163
	v_add_u32_e32 v180, s68, v163
	ds_read_b128 v[146:149], v158
	ds_read_b128 v[150:153], v158 offset:1024
	ds_read_b128 v[154:157], v158 offset:2048
	ds_read_b128 v[158:161], v158 offset:3072
	ds_read_b128 v[168:171], v180
	ds_read_b128 v[172:175], v180 offset:1024
	ds_read_b128 v[176:179], v180 offset:2048
	ds_read_b128 v[180:183], v180 offset:3072
	s_add_u32 s42, s42, 0x80000
	s_addc_u32 s43, s43, 0
	s_mov_b32 m0, s48
	v_lshl_add_u64 v[224:225], s[42:43], 0, v[136:137]
	ds_read_b128 v[184:187], v166 offset:32768
	ds_read_b128 v[188:191], v166 offset:33792
	ds_read_b128 v[192:195], v166 offset:34816
	ds_read_b128 v[196:199], v166 offset:35840
	ds_read_b128 v[200:203], v166 offset:36864
	ds_read_b128 v[204:207], v166 offset:37888
	ds_read_b128 v[208:211], v166 offset:38912
	ds_read_b128 v[212:215], v166 offset:39936
	global_load_lds_dwordx4 v[224:225], off
	v_lshl_add_u64 v[224:225], s[42:43], 0, v[132:133]
	s_mov_b32 m0, s49
	s_nop 0
	global_load_lds_dwordx4 v[224:225], off
	s_waitcnt vmcnt(8)
	s_waitcnt lgkmcnt(0)
	s_barrier
	s_setprio 1
	s_waitcnt lgkmcnt(0)
	v_mfma_f32_16x16x32_bf16 v[126:129], v[146:149], v[184:187], v[126:129]
	v_mfma_f32_16x16x32_bf16 v[122:125], v[154:157], v[184:187], v[122:125]
	v_mfma_f32_16x16x32_bf16 v[118:121], v[146:149], v[192:195], v[118:121]
	v_mfma_f32_16x16x32_bf16 v[110:113], v[154:157], v[192:195], v[110:113]
	v_mfma_f32_16x16x32_bf16 v[102:105], v[146:149], v[200:203], v[102:105]
	v_mfma_f32_16x16x32_bf16 v[94:97], v[154:157], v[200:203], v[94:97]
	v_mfma_f32_16x16x32_bf16 v[86:89], v[146:149], v[208:211], v[86:89]
	v_mfma_f32_16x16x32_bf16 v[78:81], v[154:157], v[208:211], v[78:81]
	v_mfma_f32_16x16x32_bf16 v[126:129], v[150:153], v[188:191], v[126:129]
	v_mfma_f32_16x16x32_bf16 v[122:125], v[158:161], v[188:191], v[122:125]
	v_mfma_f32_16x16x32_bf16 v[118:121], v[150:153], v[196:199], v[118:121]
	v_mfma_f32_16x16x32_bf16 v[110:113], v[158:161], v[196:199], v[110:113]
	v_mfma_f32_16x16x32_bf16 v[102:105], v[150:153], v[204:207], v[102:105]
	v_mfma_f32_16x16x32_bf16 v[94:97], v[158:161], v[204:207], v[94:97]
	v_mfma_f32_16x16x32_bf16 v[86:89], v[150:153], v[212:215], v[86:89]
	v_mfma_f32_16x16x32_bf16 v[78:81], v[158:161], v[212:215], v[78:81]
	s_setprio 0
	s_setprio 1
	v_mfma_f32_16x16x32_bf16 v[114:117], v[168:171], v[184:187], v[114:117]
	v_mfma_f32_16x16x32_bf16 v[106:109], v[176:179], v[184:187], v[106:109]
	v_mfma_f32_16x16x32_bf16 v[98:101], v[168:171], v[192:195], v[98:101]
	v_mfma_f32_16x16x32_bf16 v[90:93], v[176:179], v[192:195], v[90:93]
	v_mfma_f32_16x16x32_bf16 v[82:85], v[168:171], v[200:203], v[82:85]
	v_mfma_f32_16x16x32_bf16 v[74:77], v[176:179], v[200:203], v[74:77]
	v_mfma_f32_16x16x32_bf16 v[70:73], v[168:171], v[208:211], v[70:73]
	v_mfma_f32_16x16x32_bf16 v[66:69], v[176:179], v[208:211], v[66:69]
	v_mfma_f32_16x16x32_bf16 v[114:117], v[172:175], v[188:191], v[114:117]
	v_mfma_f32_16x16x32_bf16 v[106:109], v[180:183], v[188:191], v[106:109]
	v_mfma_f32_16x16x32_bf16 v[98:101], v[172:175], v[196:199], v[98:101]
	v_mfma_f32_16x16x32_bf16 v[90:93], v[180:183], v[196:199], v[90:93]
	v_mfma_f32_16x16x32_bf16 v[82:85], v[172:175], v[204:207], v[82:85]
	v_mfma_f32_16x16x32_bf16 v[74:77], v[180:183], v[204:207], v[74:77]
	v_mfma_f32_16x16x32_bf16 v[70:73], v[172:175], v[212:215], v[70:73]
	v_mfma_f32_16x16x32_bf16 v[66:69], v[180:183], v[212:215], v[66:69]
	s_setprio 0
	s_barrier
	s_add_i32 s42, s67, s33
	v_lshl_add_u64 v[216:217], v[216:217], 0, s[12:13]
	s_mov_b32 m0, s42
	ds_read_b128 v[184:187], v166 offset:49152
	ds_read_b128 v[188:191], v166 offset:50176
	ds_read_b128 v[192:195], v166 offset:51200
	ds_read_b128 v[196:199], v166 offset:52224
	ds_read_b128 v[200:203], v166 offset:53248
	ds_read_b128 v[204:207], v166 offset:54272
	ds_read_b128 v[208:211], v166 offset:55296
	ds_read_b128 v[212:215], v166 offset:56320
	global_load_lds_dwordx4 v[216:217], off
	s_add_i32 m0, s42, 0x2000
	s_add_u32 s40, s40, 0x80080
	v_lshl_add_u64 v[216:217], v[218:219], 0, s[12:13]
	s_addc_u32 s41, s41, 0
	s_add_i32 s42, s68, s33
	global_load_lds_dwordx4 v[216:217], off
	v_lshl_add_u64 v[216:217], s[40:41], 0, v[134:135]
	s_mov_b32 m0, s42
	s_nop 0
	global_load_lds_dwordx4 v[216:217], off
	v_lshl_add_u64 v[216:217], s[40:41], 0, v[130:131]
	s_add_i32 m0, s42, 0x2000
	s_nop 0
	global_load_lds_dwordx4 v[216:217], off
	v_lshl_add_u64 v[216:217], v[220:221], 0, s[12:13]
	s_mov_b32 m0, s53
	s_nop 0
	global_load_lds_dwordx4 v[216:217], off
	v_lshl_add_u64 v[216:217], v[222:223], 0, s[12:13]
	s_mov_b32 m0, s54
	s_nop 0
	global_load_lds_dwordx4 v[216:217], off
	s_waitcnt vmcnt(8)
	s_waitcnt lgkmcnt(0)
	s_barrier
	s_setprio 1
	s_waitcnt lgkmcnt(0)
	v_mfma_f32_16x16x32_bf16 v[62:65], v[146:149], v[184:187], v[62:65]
	v_mfma_f32_16x16x32_bf16 v[58:61], v[154:157], v[184:187], v[58:61]
	v_mfma_f32_16x16x32_bf16 v[54:57], v[146:149], v[192:195], v[54:57]
	v_mfma_f32_16x16x32_bf16 v[46:49], v[154:157], v[192:195], v[46:49]
	v_mfma_f32_16x16x32_bf16 v[38:41], v[146:149], v[200:203], v[38:41]
	v_mfma_f32_16x16x32_bf16 v[30:33], v[154:157], v[200:203], v[30:33]
	v_mfma_f32_16x16x32_bf16 v[22:25], v[146:149], v[208:211], v[22:25]
	v_mfma_f32_16x16x32_bf16 v[14:17], v[154:157], v[208:211], v[14:17]
	v_mfma_f32_16x16x32_bf16 v[62:65], v[150:153], v[188:191], v[62:65]
	v_mfma_f32_16x16x32_bf16 v[58:61], v[158:161], v[188:191], v[58:61]
	v_mfma_f32_16x16x32_bf16 v[54:57], v[150:153], v[196:199], v[54:57]
	v_mfma_f32_16x16x32_bf16 v[46:49], v[158:161], v[196:199], v[46:49]
	v_mfma_f32_16x16x32_bf16 v[38:41], v[150:153], v[204:207], v[38:41]
	v_mfma_f32_16x16x32_bf16 v[30:33], v[158:161], v[204:207], v[30:33]
	v_mfma_f32_16x16x32_bf16 v[22:25], v[150:153], v[212:215], v[22:25]
	v_mfma_f32_16x16x32_bf16 v[14:17], v[158:161], v[212:215], v[14:17]
	s_setprio 0
	s_setprio 1
	v_mfma_f32_16x16x32_bf16 v[50:53], v[168:171], v[184:187], v[50:53]
	v_mfma_f32_16x16x32_bf16 v[42:45], v[176:179], v[184:187], v[42:45]
	v_mfma_f32_16x16x32_bf16 v[34:37], v[168:171], v[192:195], v[34:37]
	v_mfma_f32_16x16x32_bf16 v[26:29], v[176:179], v[192:195], v[26:29]
	v_mfma_f32_16x16x32_bf16 v[18:21], v[168:171], v[200:203], v[18:21]
	v_mfma_f32_16x16x32_bf16 v[10:13], v[176:179], v[200:203], v[10:13]
	v_mfma_f32_16x16x32_bf16 v[6:9], v[168:171], v[208:211], v[6:9]
	v_mfma_f32_16x16x32_bf16 v[2:5], v[176:179], v[208:211], v[2:5]
	v_mfma_f32_16x16x32_bf16 v[50:53], v[172:175], v[188:191], v[50:53]
	v_mfma_f32_16x16x32_bf16 v[42:45], v[180:183], v[188:191], v[42:45]
	v_mfma_f32_16x16x32_bf16 v[34:37], v[172:175], v[196:199], v[34:37]
	v_mfma_f32_16x16x32_bf16 v[26:29], v[180:183], v[196:199], v[26:29]
	v_mfma_f32_16x16x32_bf16 v[18:21], v[172:175], v[204:207], v[18:21]
	v_mfma_f32_16x16x32_bf16 v[10:13], v[180:183], v[204:207], v[10:13]
	v_mfma_f32_16x16x32_bf16 v[6:9], v[172:175], v[212:215], v[6:9]
	v_mfma_f32_16x16x32_bf16 v[2:5], v[180:183], v[212:215], v[2:5]
	s_setprio 0
	s_barrier
	s_add_i32 s66, s66, 2
	s_add_u32 s8, s8, 0x100
	s_addc_u32 s9, s9, 0
	s_add_u32 s64, s64, 0x100
	s_addc_u32 s65, s65, 0
	s_cmp_gt_u32 s66, 29
	s_cbranch_scc0 .LBB0_3201
	s_mov_b32 s32, 1
	s_and_b64 vcc, exec, s[14:15]
	s_cbranch_vccz .LBB0_3204
	s_barrier

.LBB0_3402:
	s_and_b64 vcc, exec, s[0:1]
	s_cbranch_vccz .LBB0_3465
	s_mov_b32 s32, 0
	s_cmpk_lt_i32 s86, 0x200
	s_cselect_b64 s[0:1], -1, 0
	s_cmpk_gt_i32 s86, 0x1ff
	v_readfirstlane_b32 s6, v0
	s_cbranch_scc1 .LBB0_3409
	s_ashr_i32 s2, s86, 31
	s_lshr_b32 s2, s2, 29
	s_add_i32 s7, s86, s2
	s_and_b32 s2, s7, -8
	s_sub_i32 s8, s86, s2
	s_cmp_gt_i32 s8, -1
	s_cbranch_scc0 .LBB0_3406
	s_lshl_b32 s9, s8, 6
	s_cbranch_execz .LBB0_3407
	s_branch .LBB0_3408

.LBB0_3426:
	ds_read_b128 v[140:143], v181
	ds_read_b128 v[144:147], v181 offset:1024
	ds_read_b128 v[148:151], v181 offset:2048
	ds_read_b128 v[152:155], v181 offset:3072
	ds_read_b128 v[156:159], v182
	ds_read_b128 v[160:163], v182 offset:1024
	ds_read_b128 v[164:167], v182 offset:2048
	ds_read_b128 v[168:171], v182 offset:3072
	s_add_u32 s6, s40, 0x100
	s_addc_u32 s7, s41, 0
	s_cmpk_eq_i32 s68, 0x54
	s_cselect_b32 s45, s37, s7
	s_cselect_b32 s44, s36, s6
	s_cselect_b32 s43, s39, s67
	s_cselect_b32 s42, s38, s66
	v_lshl_add_u64 v[176:177], s[40:41], 0, v[132:133]
	s_add_i32 m0, s23, 0xc000
	ds_read_b128 v[172:175], v183
	ds_read_b128 v[186:189], v183 offset:1024
	ds_read_b128 v[190:193], v183 offset:2048
	ds_read_b128 v[194:197], v183 offset:3072
	ds_read_b128 v[198:201], v183 offset:4096
	ds_read_b128 v[202:205], v183 offset:5120
	ds_read_b128 v[206:209], v183 offset:6144
	ds_read_b128 v[210:213], v183 offset:7168
	global_load_lds_dwordx4 v[176:177], off
	v_lshl_add_u64 v[176:177], s[40:41], 0, v[134:135]
	s_add_i32 m0, s23, 0xe000
	s_nop 0
	global_load_lds_dwordx4 v[176:177], off
	s_cmp_lg_u32 s32, 0
	s_cbranch_scc1 .Lkw_P14_1
	s_waitcnt vmcnt(8)
.Lkw_P14_1:
	s_waitcnt lgkmcnt(0)
	s_barrier
	s_setprio 1
	s_waitcnt lgkmcnt(0)
	v_mfma_f32_16x16x32_bf16 v[124:127], v[140:143], v[172:175], v[124:127]
	v_mfma_f32_16x16x32_bf16 v[120:123], v[148:151], v[172:175], v[120:123]
	v_mfma_f32_16x16x32_bf16 v[108:111], v[140:143], v[190:193], v[108:111]
	v_mfma_f32_16x16x32_bf16 v[104:107], v[148:151], v[190:193], v[104:107]
	v_mfma_f32_16x16x32_bf16 v[92:95], v[140:143], v[198:201], v[92:95]
	v_mfma_f32_16x16x32_bf16 v[88:91], v[148:151], v[198:201], v[88:91]
	v_mfma_f32_16x16x32_bf16 v[76:79], v[140:143], v[206:209], v[76:79]
	v_mfma_f32_16x16x32_bf16 v[72:75], v[148:151], v[206:209], v[72:75]
	v_mfma_f32_16x16x32_bf16 v[124:127], v[144:147], v[186:189], v[124:127]
	v_mfma_f32_16x16x32_bf16 v[120:123], v[152:155], v[186:189], v[120:123]
	v_mfma_f32_16x16x32_bf16 v[108:111], v[144:147], v[194:197], v[108:111]
	v_mfma_f32_16x16x32_bf16 v[104:107], v[152:155], v[194:197], v[104:107]
	v_mfma_f32_16x16x32_bf16 v[92:95], v[144:147], v[202:205], v[92:95]
	v_mfma_f32_16x16x32_bf16 v[88:91], v[152:155], v[202:205], v[88:91]
	v_mfma_f32_16x16x32_bf16 v[76:79], v[144:147], v[210:213], v[76:79]
	v_mfma_f32_16x16x32_bf16 v[72:75], v[152:155], v[210:213], v[72:75]
	s_setprio 0
	s_setprio 1
	v_mfma_f32_16x16x32_bf16 v[116:119], v[156:159], v[172:175], v[116:119]
	v_mfma_f32_16x16x32_bf16 v[112:115], v[164:167], v[172:175], v[112:115]
	v_mfma_f32_16x16x32_bf16 v[100:103], v[156:159], v[190:193], v[100:103]
	v_mfma_f32_16x16x32_bf16 v[96:99], v[164:167], v[190:193], v[96:99]
	v_mfma_f32_16x16x32_bf16 v[84:87], v[156:159], v[198:201], v[84:87]
	v_mfma_f32_16x16x32_bf16 v[80:83], v[164:167], v[198:201], v[80:83]
	v_mfma_f32_16x16x32_bf16 v[68:71], v[156:159], v[206:209], v[68:71]
	v_mfma_f32_16x16x32_bf16 v[64:67], v[164:167], v[206:209], v[64:67]
	v_mfma_f32_16x16x32_bf16 v[116:119], v[160:163], v[186:189], v[116:119]
	v_mfma_f32_16x16x32_bf16 v[112:115], v[168:171], v[186:189], v[112:115]
	v_mfma_f32_16x16x32_bf16 v[100:103], v[160:163], v[194:197], v[100:103]
	v_mfma_f32_16x16x32_bf16 v[96:99], v[168:171], v[194:197], v[96:99]
	v_mfma_f32_16x16x32_bf16 v[84:87], v[160:163], v[202:205], v[84:87]
	v_mfma_f32_16x16x32_bf16 v[80:83], v[168:171], v[202:205], v[80:83]
	v_mfma_f32_16x16x32_bf16 v[68:71], v[160:163], v[210:213], v[68:71]
	v_mfma_f32_16x16x32_bf16 v[64:67], v[168:171], v[210:213], v[64:67]
	s_setprio 0
	s_barrier
	s_add_i32 s40, s59, s21
	v_lshl_add_u64 v[176:177], s[42:43], 0, v[128:129]
	s_mov_b32 m0, s40
	ds_read_b128 v[172:175], v183 offset:16384
	ds_read_b128 v[186:189], v183 offset:17408
	ds_read_b128 v[190:193], v183 offset:18432
	ds_read_b128 v[194:197], v183 offset:19456
	ds_read_b128 v[198:201], v183 offset:20480
	ds_read_b128 v[202:205], v183 offset:21504
	ds_read_b128 v[206:209], v183 offset:22528
	ds_read_b128 v[210:213], v183 offset:23552
	global_load_lds_dwordx4 v[176:177], off
	s_add_i32 m0, s40, 0x2000
	s_add_u32 s40, s42, 0x160000
	v_lshl_add_u64 v[214:215], s[42:43], 0, v[130:131]
	s_addc_u32 s41, s43, 0
	s_add_i32 s69, s60, s21
	global_load_lds_dwordx4 v[214:215], off
	v_lshl_add_u64 v[216:217], s[40:41], 0, v[128:129]
	s_mov_b32 m0, s69
	v_lshl_add_u64 v[218:219], s[44:45], 0, v[130:131]
	global_load_lds_dwordx4 v[216:217], off
	v_lshl_add_u64 v[216:217], s[40:41], 0, v[130:131]
	s_add_i32 m0, s69, 0x2000
	s_nop 0
	global_load_lds_dwordx4 v[216:217], off
	v_lshl_add_u64 v[216:217], s[44:45], 0, v[128:129]
	s_mov_b32 m0, s23
	s_nop 0
	global_load_lds_dwordx4 v[216:217], off
	s_mov_b32 m0, s47
	s_nop 0
	global_load_lds_dwordx4 v[218:219], off
	s_cmp_lg_u32 s32, 0
	s_cbranch_scc1 .Lkw_P14_2
	s_waitcnt vmcnt(8)
.Lkw_P14_2:
	s_mov_b32 s32, 0
	s_waitcnt lgkmcnt(0)
	s_barrier
	s_setprio 1
	s_waitcnt lgkmcnt(0)
	v_mfma_f32_16x16x32_bf16 v[60:63], v[140:143], v[172:175], v[60:63]
	v_mfma_f32_16x16x32_bf16 v[56:59], v[148:151], v[172:175], v[56:59]
	v_mfma_f32_16x16x32_bf16 v[44:47], v[140:143], v[190:193], v[44:47]
	v_mfma_f32_16x16x32_bf16 v[40:43], v[148:151], v[190:193], v[40:43]
	v_mfma_f32_16x16x32_bf16 v[28:31], v[140:143], v[198:201], v[28:31]
	v_mfma_f32_16x16x32_bf16 v[24:27], v[148:151], v[198:201], v[24:27]
	v_mfma_f32_16x16x32_bf16 v[12:15], v[140:143], v[206:209], v[12:15]
	v_mfma_f32_16x16x32_bf16 v[8:11], v[148:151], v[206:209], v[8:11]
	v_mfma_f32_16x16x32_bf16 v[60:63], v[144:147], v[186:189], v[60:63]
	v_mfma_f32_16x16x32_bf16 v[56:59], v[152:155], v[186:189], v[56:59]
	v_mfma_f32_16x16x32_bf16 v[44:47], v[144:147], v[194:197], v[44:47]
	v_mfma_f32_16x16x32_bf16 v[40:43], v[152:155], v[194:197], v[40:43]
	v_mfma_f32_16x16x32_bf16 v[28:31], v[144:147], v[202:205], v[28:31]
	v_mfma_f32_16x16x32_bf16 v[24:27], v[152:155], v[202:205], v[24:27]
	v_mfma_f32_16x16x32_bf16 v[12:15], v[144:147], v[210:213], v[12:15]
	v_mfma_f32_16x16x32_bf16 v[8:11], v[152:155], v[210:213], v[8:11]
	s_setprio 0
	s_setprio 1
	v_mfma_f32_16x16x32_bf16 v[52:55], v[156:159], v[172:175], v[52:55]
	v_mfma_f32_16x16x32_bf16 v[48:51], v[164:167], v[172:175], v[48:51]
	v_mfma_f32_16x16x32_bf16 v[36:39], v[156:159], v[190:193], v[36:39]
	v_mfma_f32_16x16x32_bf16 v[32:35], v[164:167], v[190:193], v[32:35]
	v_mfma_f32_16x16x32_bf16 v[20:23], v[156:159], v[198:201], v[20:23]
	v_mfma_f32_16x16x32_bf16 v[16:19], v[164:167], v[198:201], v[16:19]
	v_mfma_f32_16x16x32_bf16 v[4:7], v[156:159], v[206:209], v[4:7]
	v_mfma_f32_16x16x32_bf16 v[0:3], v[164:167], v[206:209], v[0:3]
	v_mfma_f32_16x16x32_bf16 v[52:55], v[160:163], v[186:189], v[52:55]
	v_mfma_f32_16x16x32_bf16 v[48:51], v[168:171], v[186:189], v[48:51]
	v_mfma_f32_16x16x32_bf16 v[36:39], v[160:163], v[194:197], v[36:39]
	v_mfma_f32_16x16x32_bf16 v[32:35], v[168:171], v[194:197], v[32:35]
	v_mfma_f32_16x16x32_bf16 v[20:23], v[160:163], v[202:205], v[20:23]
	v_mfma_f32_16x16x32_bf16 v[16:19], v[168:171], v[202:205], v[16:19]
	v_mfma_f32_16x16x32_bf16 v[4:7], v[160:163], v[210:213], v[4:7]
	v_mfma_f32_16x16x32_bf16 v[0:3], v[168:171], v[210:213], v[0:3]
	s_setprio 0
	s_barrier
	s_add_i32 s69, 0, 0x18000
	s_add_i32 s70, 0, 0x1c000
	v_add_u32_e32 v152, s69, v180
	v_add_u32_e32 v168, s70, v180
	ds_read_b128 v[140:143], v152
	ds_read_b128 v[144:147], v152 offset:1024
	ds_read_b128 v[148:151], v152 offset:2048
	ds_read_b128 v[152:155], v152 offset:3072
	ds_read_b128 v[156:159], v168
	ds_read_b128 v[160:163], v168 offset:1024
	ds_read_b128 v[164:167], v168 offset:2048
	ds_read_b128 v[168:171], v168 offset:3072
	s_add_u32 s40, s44, 0x160000
	s_addc_u32 s41, s45, 0
	s_mov_b32 m0, s48
	v_lshl_add_u64 v[220:221], s[40:41], 0, v[128:129]
	ds_read_b128 v[172:175], v183 offset:32768
	ds_read_b128 v[186:189], v183 offset:33792
	ds_read_b128 v[190:193], v183 offset:34816
	ds_read_b128 v[194:197], v183 offset:35840
	ds_read_b128 v[198:201], v183 offset:36864
	ds_read_b128 v[202:205], v183 offset:37888
	ds_read_b128 v[206:209], v183 offset:38912
	ds_read_b128 v[210:213], v183 offset:39936
	global_load_lds_dwordx4 v[220:221], off
	v_lshl_add_u64 v[220:221], s[40:41], 0, v[130:131]
	s_mov_b32 m0, s49
	s_nop 0
	global_load_lds_dwordx4 v[220:221], off
	s_waitcnt vmcnt(8)
	s_waitcnt lgkmcnt(0)
	s_barrier
	s_setprio 1
	s_waitcnt lgkmcnt(0)
	v_mfma_f32_16x16x32_bf16 v[124:127], v[140:143], v[172:175], v[124:127]
	v_mfma_f32_16x16x32_bf16 v[120:123], v[148:151], v[172:175], v[120:123]
	v_mfma_f32_16x16x32_bf16 v[108:111], v[140:143], v[190:193], v[108:111]
	v_mfma_f32_16x16x32_bf16 v[104:107], v[148:151], v[190:193], v[104:107]
	v_mfma_f32_16x16x32_bf16 v[92:95], v[140:143], v[198:201], v[92:95]
	v_mfma_f32_16x16x32_bf16 v[88:91], v[148:151], v[198:201], v[88:91]
	v_mfma_f32_16x16x32_bf16 v[76:79], v[140:143], v[206:209], v[76:79]
	v_mfma_f32_16x16x32_bf16 v[72:75], v[148:151], v[206:209], v[72:75]
	v_mfma_f32_16x16x32_bf16 v[124:127], v[144:147], v[186:189], v[124:127]
	v_mfma_f32_16x16x32_bf16 v[120:123], v[152:155], v[186:189], v[120:123]
	v_mfma_f32_16x16x32_bf16 v[108:111], v[144:147], v[194:197], v[108:111]
	v_mfma_f32_16x16x32_bf16 v[104:107], v[152:155], v[194:197], v[104:107]
	v_mfma_f32_16x16x32_bf16 v[92:95], v[144:147], v[202:205], v[92:95]
	v_mfma_f32_16x16x32_bf16 v[88:91], v[152:155], v[202:205], v[88:91]
	v_mfma_f32_16x16x32_bf16 v[76:79], v[144:147], v[210:213], v[76:79]
	v_mfma_f32_16x16x32_bf16 v[72:75], v[152:155], v[210:213], v[72:75]
	s_setprio 0
	s_setprio 1
	v_mfma_f32_16x16x32_bf16 v[116:119], v[156:159], v[172:175], v[116:119]
	v_mfma_f32_16x16x32_bf16 v[112:115], v[164:167], v[172:175], v[112:115]
	v_mfma_f32_16x16x32_bf16 v[100:103], v[156:159], v[190:193], v[100:103]
	v_mfma_f32_16x16x32_bf16 v[96:99], v[164:167], v[190:193], v[96:99]
	v_mfma_f32_16x16x32_bf16 v[84:87], v[156:159], v[198:201], v[84:87]
	v_mfma_f32_16x16x32_bf16 v[80:83], v[164:167], v[198:201], v[80:83]
	v_mfma_f32_16x16x32_bf16 v[68:71], v[156:159], v[206:209], v[68:71]
	v_mfma_f32_16x16x32_bf16 v[64:67], v[164:167], v[206:209], v[64:67]
	v_mfma_f32_16x16x32_bf16 v[116:119], v[160:163], v[186:189], v[116:119]
	v_mfma_f32_16x16x32_bf16 v[112:115], v[168:171], v[186:189], v[112:115]
	v_mfma_f32_16x16x32_bf16 v[100:103], v[160:163], v[194:197], v[100:103]
	v_mfma_f32_16x16x32_bf16 v[96:99], v[168:171], v[194:197], v[96:99]
	v_mfma_f32_16x16x32_bf16 v[84:87], v[160:163], v[202:205], v[84:87]
	v_mfma_f32_16x16x32_bf16 v[80:83], v[168:171], v[202:205], v[80:83]
	v_mfma_f32_16x16x32_bf16 v[68:71], v[160:163], v[210:213], v[68:71]
	v_mfma_f32_16x16x32_bf16 v[64:67], v[168:171], v[210:213], v[64:67]
	s_setprio 0
	s_barrier
	s_add_i32 s40, s69, s21
	v_lshl_add_u64 v[176:177], v[176:177], 0, s[14:15]
	s_mov_b32 m0, s40
	ds_read_b128 v[172:175], v183 offset:49152
	ds_read_b128 v[186:189], v183 offset:50176
	ds_read_b128 v[190:193], v183 offset:51200
	ds_read_b128 v[194:197], v183 offset:52224
	ds_read_b128 v[198:201], v183 offset:53248
	ds_read_b128 v[202:205], v183 offset:54272
	ds_read_b128 v[206:209], v183 offset:55296
	ds_read_b128 v[210:213], v183 offset:56320
	global_load_lds_dwordx4 v[176:177], off
	s_add_i32 m0, s40, 0x2000
	s_add_u32 s40, s42, 0x160080
	v_lshl_add_u64 v[176:177], v[214:215], 0, s[14:15]
	s_addc_u32 s41, s43, 0
	s_add_i32 s42, s70, s21
	global_load_lds_dwordx4 v[176:177], off
	v_lshl_add_u64 v[176:177], s[40:41], 0, v[128:129]
	s_mov_b32 m0, s42
	s_nop 0
	global_load_lds_dwordx4 v[176:177], off
	v_lshl_add_u64 v[176:177], s[40:41], 0, v[130:131]
	s_add_i32 m0, s42, 0x2000
	s_nop 0
	global_load_lds_dwordx4 v[176:177], off
	v_lshl_add_u64 v[176:177], v[216:217], 0, s[14:15]
	s_mov_b32 m0, s56
	s_nop 0
	global_load_lds_dwordx4 v[176:177], off
	v_lshl_add_u64 v[176:177], v[218:219], 0, s[14:15]
	s_mov_b32 m0, s57
	s_nop 0
	global_load_lds_dwordx4 v[176:177], off
	s_waitcnt vmcnt(8)
	s_waitcnt lgkmcnt(0)
	s_barrier
	s_setprio 1
	s_waitcnt lgkmcnt(0)
	v_mfma_f32_16x16x32_bf16 v[60:63], v[140:143], v[172:175], v[60:63]
	v_mfma_f32_16x16x32_bf16 v[56:59], v[148:151], v[172:175], v[56:59]
	v_mfma_f32_16x16x32_bf16 v[44:47], v[140:143], v[190:193], v[44:47]
	v_mfma_f32_16x16x32_bf16 v[40:43], v[148:151], v[190:193], v[40:43]
	v_mfma_f32_16x16x32_bf16 v[28:31], v[140:143], v[198:201], v[28:31]
	v_mfma_f32_16x16x32_bf16 v[24:27], v[148:151], v[198:201], v[24:27]
	v_mfma_f32_16x16x32_bf16 v[12:15], v[140:143], v[206:209], v[12:15]
	v_mfma_f32_16x16x32_bf16 v[8:11], v[148:151], v[206:209], v[8:11]
	v_mfma_f32_16x16x32_bf16 v[60:63], v[144:147], v[186:189], v[60:63]
	v_mfma_f32_16x16x32_bf16 v[56:59], v[152:155], v[186:189], v[56:59]
	v_mfma_f32_16x16x32_bf16 v[44:47], v[144:147], v[194:197], v[44:47]
	v_mfma_f32_16x16x32_bf16 v[40:43], v[152:155], v[194:197], v[40:43]
	v_mfma_f32_16x16x32_bf16 v[28:31], v[144:147], v[202:205], v[28:31]
	v_mfma_f32_16x16x32_bf16 v[24:27], v[152:155], v[202:205], v[24:27]
	v_mfma_f32_16x16x32_bf16 v[12:15], v[144:147], v[210:213], v[12:15]
	v_mfma_f32_16x16x32_bf16 v[8:11], v[152:155], v[210:213], v[8:11]
	s_setprio 0
	s_setprio 1
	v_mfma_f32_16x16x32_bf16 v[52:55], v[156:159], v[172:175], v[52:55]
	v_mfma_f32_16x16x32_bf16 v[48:51], v[164:167], v[172:175], v[48:51]
	v_mfma_f32_16x16x32_bf16 v[36:39], v[156:159], v[190:193], v[36:39]
	v_mfma_f32_16x16x32_bf16 v[32:35], v[164:167], v[190:193], v[32:35]
	v_mfma_f32_16x16x32_bf16 v[20:23], v[156:159], v[198:201], v[20:23]
	v_mfma_f32_16x16x32_bf16 v[16:19], v[164:167], v[198:201], v[16:19]
	v_mfma_f32_16x16x32_bf16 v[4:7], v[156:159], v[206:209], v[4:7]
	v_mfma_f32_16x16x32_bf16 v[0:3], v[164:167], v[206:209], v[0:3]
	v_mfma_f32_16x16x32_bf16 v[52:55], v[160:163], v[186:189], v[52:55]
	v_mfma_f32_16x16x32_bf16 v[48:51], v[168:171], v[186:189], v[48:51]
	v_mfma_f32_16x16x32_bf16 v[36:39], v[160:163], v[194:197], v[36:39]
	v_mfma_f32_16x16x32_bf16 v[32:35], v[168:171], v[194:197], v[32:35]
	v_mfma_f32_16x16x32_bf16 v[20:23], v[160:163], v[202:205], v[20:23]
	v_mfma_f32_16x16x32_bf16 v[16:19], v[168:171], v[202:205], v[16:19]
	v_mfma_f32_16x16x32_bf16 v[4:7], v[160:163], v[210:213], v[4:7]
	v_mfma_f32_16x16x32_bf16 v[0:3], v[168:171], v[210:213], v[0:3]
	s_setprio 0
	s_barrier
	s_add_i32 s68, s68, 2
	s_add_u32 s66, s66, 0x100
	s_addc_u32 s67, s67, 0
	s_cmpk_gt_u32 s68, 0x55
	s_mov_b64 s[40:41], s[6:7]
	s_cbranch_scc0 .LBB0_3426
	s_mov_b32 s32, 1
	s_and_b64 vcc, exec, s[18:19]
	s_cbranch_vccz .LBB0_3429
	s_barrier
